# P11 epilogue: chunk-1 row-group-0 W_s fragment + bias loads issued before the chunk-1 normalisation into dead registers, moved in at the old site
# speedup vs baseline: 1.0105x; 1.0013x over previous
; #define GAS __attribute__((address_space(1)))
; __device__ __forceinline__ int my_tid() { int t = threadIdx.x; asm volatile("" : "+v"(t)); return t; }
;     __device__ __forceinline__ void operator()(const af4 (&acc)[2][2][4][2], const pg8::Unit& u, int wr_, int wc_, int fr_, int fq_) const {
;         const int tid = my_tid(), lane = tid & 63, wid = __builtin_amdgcn_readfirstlane(tid >> 6), wr = wid >> 2, wc = wid & 3, fr = lane & 15, fq = lane >> 4;
;         (void)wr_; (void)wc_; (void)fr_; (void)fq_;
;         const int chbase = u.pn * 128, grp = u.pn / 6;
;         const bf16* wsg = wsb + (size_t)grp * 128 * 128;
;         const int chl = chbase + 32 * wc + 8 * (fr >> 2) + (fr & 3);
;         float lg[2], lb[2];
; #pragma unroll
;         for (int n = 0; n < 2; ++n) { lg[n] = lng[chl + 4 * n]; lb[n] = lnb[chl + 4 * n]; }
;         v4u raw[2][4];
;         auto load_raw = [&](int ai) {
; #pragma unroll
;             for (int ks = 0; ks < 4; ++ks)
; #pragma unroll
;                 for (int n = 0; n < 2; ++n) raw[n][ks] = *(const GAS v4u*)(VT + (size_t)(chl + 4 * n) * MLAT + u.pm * 256 + ai * 128 + 32 * ks + 8 * fq);
;         };
;         load_raw(0);
;     ...
;                 const float bsi = bs[grp * 128 + it];
.Lp11_st_nowr:
	s_waitcnt lgkmcnt(0)
	s_barrier
	v_mov_b32_e32 v164, v0
	s_mul_hi_i32 s23, s44, 0x2aaaaaab
	s_lshr_b32 s26, s23, 31
	v_readfirstlane_b32 s25, v164
	v_lshlrev_b32_e32 v130, 1, v164
	s_lshl_b32 s40, s44, 7
	s_add_i32 s44, s23, s26
	s_lshr_b32 s23, s25, 1
	v_and_b32_e32 v130, 24, v130
	v_and_b32_e32 v131, 3, v164
	s_ashr_i32 s45, s44, 31
	s_and_b32 s23, s23, 0x60
	v_or3_b32 v130, v131, v130, s40
	s_lshl_b64 s[26:27], s[44:45], 15
	v_or_b32_e32 v146, s23, v130
	v_or_b32_e32 v134, 4, v146
	s_add_u32 s52, s62, s26
	v_ashrrev_i32_e32 v147, 31, v146
	v_ashrrev_i32_e32 v135, 31, v134
	s_addc_u32 s53, s63, s27
	s_lshl_b32 s42, s6, 8
	v_lshrrev_b32_e32 v132, 1, v164
	v_lshlrev_b64 v[130:131], 15, v[146:147]
	s_ashr_i32 s43, s42, 31
	v_and_b32_e32 v209, 24, v132
	v_lshlrev_b64 v[134:135], 15, v[134:135]
	v_lshl_add_u64 v[130:131], s[50:51], 0, v[130:131]
	s_lshl_b64 s[26:27], s[42:43], 1
	v_lshl_add_u64 v[134:135], s[50:51], 0, v[134:135]
	v_or_b32_e32 v162, s42, v209
	v_lshl_add_u64 v[130:131], v[130:131], 0, s[26:27]
	v_lshlrev_b32_e32 v186, 1, v209
	v_lshl_add_u64 v[148:149], v[134:135], 0, s[26:27]
	v_ashrrev_i32_e32 v163, 31, v162
	v_lshl_add_u64 v[216:217], v[130:131], 0, v[186:187]
	v_lshl_add_u32 v150, v162, 3, s98
	v_lshl_add_u64 v[220:221], v[148:149], 0, v[186:187]
	v_mov_b64_e32 v[130:131], v[192:193]
	v_mov_b64_e32 v[132:133], v[194:195]
	ds_read_b128 v[134:137], v150 offset:16
	ds_read_b128 v[138:141], v150
	ds_read_b128 v[142:145], v150 offset:48
	ds_read_b128 v[166:169], v150 offset:32
	v_mov_b64_e32 v[170:171], v[222:223]
	v_mov_b64_e32 v[172:173], v[224:225]
	v_readlane_b32 s80, v254, 2
	v_readlane_b32 s81, v254, 3
	v_readlane_b32 s90, v254, 12
	v_readlane_b32 s91, v254, 13
	v_readlane_b32 s92, v254, 14
	v_readlane_b32 s93, v254, 15
	v_lshlrev_b64 v[146:147], 2, v[146:147]
	s_mov_b64 s[78:79], s[90:91]
	s_mov_b64 s[80:81], s[92:93]
	v_lshl_add_u64 v[148:149], s[78:79], 0, v[146:147]
	v_lshl_add_u64 v[146:147], s[80:81], 0, v[146:147]
	v_mov_b32_e32 v206, v183
	v_mov_b32_e32 v208, v179
	v_mov_b32_e32 v202, v181
	v_mov_b32_e32 v204, v185
	s_mov_b32 s100, 0x20800
	s_mov_b32 s101, 0x24000
	s_bitcmp1_b32 s25, 8
	s_cselect_b32 s100, s101, s100
	v_and_b32_e32 v189, 63, v0
	v_lshl_add_u32 v189, v189, 4, s100
	s_lshr_b32 s99, s25, 2
	s_andn2_b32 s99, s99, 63
	v_and_or_b32 v185, v0, 15, s99
	v_lshl_add_u32 v185, s44, 7, v185
	v_lshlrev_b32_e32 v185, 2, v185
	global_load_dword v179, v185, s[76:77] offset:64
	global_load_dword v181, v185, s[76:77] offset:128
	global_load_dword v183, v185, s[76:77] offset:192
	v_mov_b64_e32 v[174:175], v[226:227]
	v_mov_b64_e32 v[176:177], v[228:229]
	v_mov_b64_e32 v[150:151], v[234:235]
	v_mov_b64_e32 v[152:153], v[236:237]
	v_mov_b64_e32 v[158:159], v[238:239]
	v_mov_b64_e32 v[160:161], v[240:241]
	v_mov_b64_e32 v[196:197], v[242:243]
	v_mov_b64_e32 v[198:199], v[244:245]
	s_nop 0
	v_mov_b64_e32 v[146:147], v[246:247]
	v_mov_b64_e32 v[148:149], v[248:249]
	v_mov_b64_e32 v[154:155], v[250:251]
	v_mov_b64_e32 v[156:157], v[252:253]
	s_ashr_i32 s6, s25, 2
	s_andn2_b32 s6, s6, 63
	v_pk_mul_f32 v[226:227], v[126:127], s[20:21] op_sel_hi:[1,0]
	v_pk_mul_f32 v[234:235], v[122:123], v[126:127]
	v_pk_mul_f32 v[126:127], v[128:129], s[20:21] op_sel_hi:[1,0]
	v_pk_mul_f32 v[236:237], v[124:125], v[128:129]
	v_pk_mul_f32 v[128:129], v[120:121], v[120:121]
	v_pk_mul_f32 v[228:229], v[118:119], v[118:119]
	v_pk_mul_f32 v[230:231], v[114:115], s[20:21] op_sel_hi:[1,0]
	v_pk_mul_f32 v[238:239], v[118:119], v[114:115]
	v_pk_mul_f32 v[114:115], v[116:117], s[20:21] op_sel_hi:[1,0]
	v_pk_mul_f32 v[240:241], v[120:121], v[116:117]
	v_exp_f32_e32 v126, v126
	v_exp_f32_e32 v127, v127
	v_exp_f32_e32 v114, v114
	v_exp_f32_e32 v115, v115
	s_ashr_i32 s41, s40, 31
	v_pk_add_f32 v[126:127], v[126:127], 1.0 op_sel_hi:[1,0]
	s_lshl_b64 s[40:41], s[40:41], 1
	v_pk_add_f32 v[114:115], v[114:115], 1.0 op_sel_hi:[1,0]
	v_pk_mul_f32 v[252:253], v[102:103], v[98:99]
	v_pk_mul_f32 v[192:193], v[104:105], v[100:101]
	s_andn2_b64 vcc, exec, s[4:5]
	v_readlane_b32 s82, v254, 4
	v_readlane_b32 s83, v254, 5
	v_readlane_b32 s84, v254, 6
	v_readlane_b32 s85, v254, 7
	v_readlane_b32 s86, v254, 8
	v_readlane_b32 s87, v254, 9
	v_readlane_b32 s88, v254, 10
	v_readlane_b32 s89, v254, 11
	v_readlane_b32 s94, v254, 16
	v_readlane_b32 s95, v254, 17
	s_waitcnt vmcnt(8)
	s_waitcnt lgkmcnt(0)
; #define GAS __attribute__((address_space(1)))
; __device__ __forceinline__ void unpack8(const v4u w, float (&f)[8]) { f[0] = bflo(w.x); f[1] = bfhi(w.x); f[2] = bflo(w.y); f[3] = bfhi(w.y); f[4] = bflo(w.z); f[5] = bfhi(w.z); f[6] = bflo(w.w); f[7] = bfhi(w.w); }
; __device__ __forceinline__ v4u pack8(const float (&f)[8]) { v4u w; w.x = pk2(f[0], f[1]); w.y = pk2(f[2], f[3]); w.z = pk2(f[4], f[5]); w.w = pk2(f[6], f[7]); return w; }
;     __device__ __forceinline__ void operator()(const af4 (&acc)[2][2][4][2], const pg8::Unit& u, int wr_, int wc_, int fr_, int fq_) const {
;     ...
; #pragma unroll
;         for (int ai = 0; ai < 2; ++ai) {
;             const int tok0 = u.pm * 256 + ai * 128;
;             bf16x8 av[2][4];
; #pragma unroll
;             for (int ks = 0; ks < 4; ++ks) {
;                 const int j0 = tok0 + 32 * ks + 8 * fq;
;                 f32x4 st[4];
; #pragma unroll
;                 for (int q = 0; q < 4; ++q) st[q] = *(const GAS f32x4*)(stats + (size_t)(j0 + 2 * q) * 2);
; #pragma unroll
;                 for (int n = 0; n < 2; ++n) {
;                     float vf[8];
;                     unpack8(raw[n][ks], vf);
; #pragma unroll
;                     for (int q = 0; q < 4; ++q) { f32x2 t = {vf[2 * q], vf[2 * q + 1]}; t = t * (f32x2){st[q].z, st[q].w} + (f32x2){st[q].x, st[q].y}; t = t * lg[n] + lb[n]; vf[2 * q] = t.x; vf[2 * q + 1] = t.y; }
;                     av[n][ks] = __builtin_bit_cast(bf16x8, pack8(vf));
;                 }
;             }
	v_lshlrev_b32_e32 v200, 16, v130
	v_and_b32_e32 v201, 0xffff0000, v130
	v_lshlrev_b32_e32 v212, 16, v170
	v_and_b32_e32 v213, 0xffff0000, v170
	v_lshlrev_b32_e32 v130, 16, v131
	v_and_b32_e32 v131, 0xffff0000, v131
	v_lshlrev_b32_e32 v210, 16, v132
	v_and_b32_e32 v211, 0xffff0000, v132
	v_lshlrev_b32_e32 v132, 16, v133
	v_and_b32_e32 v133, 0xffff0000, v133
	v_pk_fma_f32 v[200:201], v[140:141], v[200:201], v[138:139]
	v_lshlrev_b32_e32 v170, 16, v171
	v_and_b32_e32 v171, 0xffff0000, v171
	v_pk_fma_f32 v[138:139], v[140:141], v[212:213], v[138:139]
	v_pk_fma_f32 v[130:131], v[136:137], v[130:131], v[134:135]
	v_pk_fma_f32 v[210:211], v[168:169], v[210:211], v[166:167]
	v_pk_fma_f32 v[132:133], v[144:145], v[132:133], v[142:143]
	v_lshlrev_b32_e32 v214, 16, v172
	v_and_b32_e32 v215, 0xffff0000, v172
	v_lshlrev_b32_e32 v172, 16, v173
	v_and_b32_e32 v173, 0xffff0000, v173
	v_pk_fma_f32 v[134:135], v[136:137], v[170:171], v[134:135]
	v_pk_fma_f32 v[138:139], v[202:203], v[138:139], v[204:205] op_sel_hi:[0,1,0]
	v_pk_fma_f32 v[200:201], v[208:209], v[200:201], v[206:207] op_sel_hi:[0,1,0]
	v_pk_fma_f32 v[218:219], v[208:209], v[130:131], v[206:207] op_sel_hi:[0,1,0]
	v_pk_fma_f32 v[210:211], v[208:209], v[210:211], v[206:207] op_sel_hi:[0,1,0]
	v_pk_fma_f32 v[222:223], v[208:209], v[132:133], v[206:207] op_sel_hi:[0,1,0]
	v_pk_fma_f32 v[140:141], v[144:145], v[172:173], v[142:143]
	v_cvt_pk_bf16_f32 v130, v200, v201
	v_cvt_pk_bf16_f32 v131, v218, v219
	v_cvt_pk_bf16_f32 v132, v210, v211
	v_cvt_pk_bf16_f32 v133, v222, v223
	v_pk_fma_f32 v[142:143], v[202:203], v[134:135], v[204:205] op_sel_hi:[0,1,0]
	v_cvt_pk_bf16_f32 v134, v138, v139
	v_or_b32_e32 v138, 32, v162
	v_pk_fma_f32 v[136:137], v[168:169], v[214:215], v[166:167]
	v_ashrrev_i32_e32 v139, 31, v138
	v_pk_fma_f32 v[136:137], v[202:203], v[136:137], v[204:205] op_sel_hi:[0,1,0]
	v_pk_fma_f32 v[140:141], v[202:203], v[140:141], v[204:205] op_sel_hi:[0,1,0]
	v_lshl_add_u32 v170, v138, 3, s98
	v_cvt_pk_bf16_f32 v135, v142, v143
	v_cvt_pk_bf16_f32 v136, v136, v137
	v_cvt_pk_bf16_f32 v137, v140, v141
	ds_read_b128 v[138:141], v170
	ds_read_b128 v[142:145], v170 offset:16
	ds_read_b128 v[166:169], v170 offset:32
	s_nop 0
	ds_read_b128 v[170:173], v170 offset:48
	v_or_b32_e32 v200, 64, v162
	v_lshlrev_b32_e32 v210, 16, v174
	v_and_b32_e32 v211, 0xffff0000, v174
	v_lshlrev_b32_e32 v174, 16, v175
	v_and_b32_e32 v175, 0xffff0000, v175
	v_lshlrev_b32_e32 v212, 16, v176
	v_and_b32_e32 v213, 0xffff0000, v176
	v_lshlrev_b32_e32 v176, 16, v177
	v_and_b32_e32 v177, 0xffff0000, v177
	v_lshlrev_b32_e32 v214, 16, v196
	v_and_b32_e32 v215, 0xffff0000, v196
	v_lshlrev_b32_e32 v196, 16, v197
	v_and_b32_e32 v197, 0xffff0000, v197
	v_lshlrev_b32_e32 v218, 16, v198
	v_and_b32_e32 v219, 0xffff0000, v198
	v_lshlrev_b32_e32 v198, 16, v199
	v_and_b32_e32 v199, 0xffff0000, v199
	v_ashrrev_i32_e32 v201, 31, v200
	v_lshl_add_u32 v200, v200, 3, s98
	v_or_b32_e32 v162, 0x60, v162
	v_ashrrev_i32_e32 v163, 31, v162
	v_lshl_add_u32 v162, v162, 3, s98
	v_and_b32_e32 v165, 0xffff0000, v160
	s_waitcnt lgkmcnt(3)
	v_pk_fma_f32 v[210:211], v[140:141], v[210:211], v[138:139]
	s_waitcnt lgkmcnt(2)
	v_pk_fma_f32 v[174:175], v[144:145], v[174:175], v[142:143]
	s_waitcnt lgkmcnt(1)
	v_pk_fma_f32 v[212:213], v[168:169], v[212:213], v[166:167]
	s_waitcnt lgkmcnt(0)
	v_pk_fma_f32 v[176:177], v[172:173], v[176:177], v[170:171]
	v_pk_fma_f32 v[138:139], v[140:141], v[214:215], v[138:139]
	v_pk_fma_f32 v[140:141], v[144:145], v[196:197], v[142:143]
	v_pk_fma_f32 v[142:143], v[168:169], v[218:219], v[166:167]
	v_pk_fma_f32 v[144:145], v[172:173], v[198:199], v[170:171]
	v_pk_fma_f32 v[166:167], v[208:209], v[210:211], v[206:207] op_sel_hi:[0,1,0]
	v_pk_fma_f32 v[168:169], v[208:209], v[174:175], v[206:207] op_sel_hi:[0,1,0]
	v_pk_fma_f32 v[170:171], v[208:209], v[212:213], v[206:207] op_sel_hi:[0,1,0]
	v_pk_fma_f32 v[172:173], v[208:209], v[176:177], v[206:207] op_sel_hi:[0,1,0]
	v_pk_fma_f32 v[138:139], v[202:203], v[138:139], v[204:205] op_sel_hi:[0,1,0]
	v_pk_fma_f32 v[140:141], v[202:203], v[140:141], v[204:205] op_sel_hi:[0,1,0]
	v_pk_fma_f32 v[174:175], v[202:203], v[142:143], v[204:205] op_sel_hi:[0,1,0]
	v_pk_fma_f32 v[176:177], v[202:203], v[144:145], v[204:205] op_sel_hi:[0,1,0]
	v_cvt_pk_bf16_f32 v142, v166, v167
	v_cvt_pk_bf16_f32 v143, v168, v169
	v_cvt_pk_bf16_f32 v144, v170, v171
	v_cvt_pk_bf16_f32 v145, v172, v173
	v_cvt_pk_bf16_f32 v138, v138, v139
	v_cvt_pk_bf16_f32 v139, v140, v141
	v_cvt_pk_bf16_f32 v140, v174, v175
	v_cvt_pk_bf16_f32 v141, v176, v177
	ds_read_b128 v[166:169], v200
	ds_read_b128 v[170:173], v200 offset:16
	ds_read_b128 v[174:177], v200 offset:32
	ds_read_b128 v[196:199], v200 offset:48
	v_lshlrev_b32_e32 v200, 16, v150
	v_and_b32_e32 v201, 0xffff0000, v150
	v_lshlrev_b32_e32 v150, 16, v151
	v_and_b32_e32 v151, 0xffff0000, v151
	v_lshlrev_b32_e32 v210, 16, v152
	v_and_b32_e32 v211, 0xffff0000, v152
	v_lshlrev_b32_e32 v152, 16, v153
	v_and_b32_e32 v153, 0xffff0000, v153
	v_lshlrev_b32_e32 v212, 16, v146
	v_and_b32_e32 v213, 0xffff0000, v146
	v_lshlrev_b32_e32 v146, 16, v147
	v_and_b32_e32 v147, 0xffff0000, v147
	v_lshlrev_b32_e32 v214, 16, v148
	v_and_b32_e32 v215, 0xffff0000, v148
	v_lshlrev_b32_e32 v148, 16, v149
	v_and_b32_e32 v149, 0xffff0000, v149
	v_lshl_add_u64 v[218:219], s[52:53], 0, v[186:187]
	s_waitcnt lgkmcnt(3)
	v_pk_fma_f32 v[200:201], v[168:169], v[200:201], v[166:167]
	s_waitcnt lgkmcnt(2)
	v_pk_fma_f32 v[150:151], v[172:173], v[150:151], v[170:171]
	s_waitcnt lgkmcnt(1)
	v_pk_fma_f32 v[210:211], v[176:177], v[210:211], v[174:175]
	s_waitcnt lgkmcnt(0)
; #define GAS __attribute__((address_space(1)))
; __device__ __forceinline__ void unpack8(const v4u w, float (&f)[8]) { f[0] = bflo(w.x); f[1] = bfhi(w.x); f[2] = bflo(w.y); f[3] = bfhi(w.y); f[4] = bflo(w.z); f[5] = bfhi(w.z); f[6] = bflo(w.w); f[7] = bfhi(w.w); }
;     __device__ __forceinline__ void operator()(const af4 (&acc)[2][2][4][2], const pg8::Unit& u, int wr_, int wc_, int fr_, int fq_) const {
;     ...
;                 for (int n = 0; n < 2; ++n) {
;                     float vf[8];
;                     unpack8(raw[n][ks], vf);
; #pragma unroll
;                     for (int q = 0; q < 4; ++q) { f32x2 t = {vf[2 * q], vf[2 * q + 1]}; t = t * (f32x2){st[q].z, st[q].w} + (f32x2){st[q].x, st[q].y}; t = t * lg[n] + lb[n]; vf[2 * q] = t.x; vf[2 * q + 1] = t.y; }
;                     av[n][ks] = __builtin_bit_cast(bf16x8, pack8(vf));
;                 }
;             }
; #pragma unroll
;             for (int m = 0; m < 4; ++m) {
;                 if (ai == 0 && m == 0) load_raw(1);
;                 const int it = wr * 64 + m * 16 + fr;
;                 bf16x8 wf[4];
; #pragma unroll
;                 for (int ks = 0; ks < 4; ++ks) wf[ks] = *(const GAS bf16x8*)(wsg + (size_t)it * 128 + 32 * ks + 8 * fq);
;                 const float bsi = bs[grp * 128 + it];
;                 af4 vm[2] = {(af4){bsi, bsi, bsi, bsi}, (af4){bsi, bsi, bsi, bsi}};
; #pragma unroll
;                 for (int ks = 0; ks < 4; ++ks) {
; #pragma unroll
;                     for (int n = 0; n < 2; ++n) vm[n] = __builtin_amdgcn_mfma_f32_16x16x32_bf16(av[n][ks], wf[ks], vm[n], 0, 0, 0);
;                 }
;                 float o[8];
; #pragma unroll
;                 for (int n = 0; n < 2; ++n)
; #pragma unroll
;                     for (int e = 0; e < 4; e += 2) {
;                         const f32x2 uu = {acc[ai][0][m][n][e], acc[ai][0][m][n][e + 1]}, gg = {acc[ai][1][m][n][e], acc[ai][1][m][n][e + 1]}, vv = {vm[n][e], vm[n][e + 1]};
;                         const f32x2 ar = uu * (uu * uu * (-2.302208198f * 0.044715f) + (-2.302208198f));
;                         const f32x2 gs = gg * (-1.4426950408889634f);
;                         const f32x2 ea = {fexp2(ar.x), fexp2(ar.y)}, eb = {fexp2(gs.x), fexp2(gs.y)};
;                         const f32x2 q = eb + 1.0f, den = ea * q + q;
;                         const f32x2 r = {frcp(den.x), frcp(den.y)};
	v_pk_fma_f32 v[152:153], v[198:199], v[152:153], v[196:197]
	v_pk_fma_f32 v[166:167], v[168:169], v[212:213], v[166:167]
	v_pk_fma_f32 v[146:147], v[172:173], v[146:147], v[170:171]
	v_pk_fma_f32 v[168:169], v[176:177], v[214:215], v[174:175]
	v_pk_fma_f32 v[148:149], v[198:199], v[148:149], v[196:197]
	v_pk_fma_f32 v[170:171], v[208:209], v[200:201], v[206:207] op_sel_hi:[0,1,0]
	v_pk_fma_f32 v[172:173], v[208:209], v[150:151], v[206:207] op_sel_hi:[0,1,0]
	v_pk_fma_f32 v[174:175], v[208:209], v[210:211], v[206:207] op_sel_hi:[0,1,0]
	v_pk_fma_f32 v[176:177], v[208:209], v[152:153], v[206:207] op_sel_hi:[0,1,0]
	v_pk_fma_f32 v[166:167], v[202:203], v[166:167], v[204:205] op_sel_hi:[0,1,0]
	v_pk_fma_f32 v[196:197], v[202:203], v[146:147], v[204:205] op_sel_hi:[0,1,0]
	v_pk_fma_f32 v[168:169], v[202:203], v[168:169], v[204:205] op_sel_hi:[0,1,0]
	v_pk_fma_f32 v[198:199], v[202:203], v[148:149], v[204:205] op_sel_hi:[0,1,0]
	v_cvt_pk_bf16_f32 v150, v170, v171
	v_cvt_pk_bf16_f32 v151, v172, v173
	v_cvt_pk_bf16_f32 v152, v174, v175
	v_cvt_pk_bf16_f32 v153, v176, v177
	v_cvt_pk_bf16_f32 v146, v166, v167
	v_cvt_pk_bf16_f32 v147, v196, v197
	v_cvt_pk_bf16_f32 v148, v168, v169
	v_cvt_pk_bf16_f32 v149, v198, v199
	ds_read_b128 v[166:169], v162
	ds_read_b128 v[170:173], v162 offset:16
	ds_read_b128 v[174:177], v162 offset:32
	ds_read_b128 v[196:199], v162 offset:48
	v_and_or_b32 v210, v164, 15, s6
	v_lshl_add_u32 v162, s44, 7, v210
	v_ashrrev_i32_e32 v163, 31, v162
	v_lshl_add_u64 v[200:201], v[162:163], 2, s[76:77]
	v_lshlrev_b32_e32 v162, 16, v158
	v_and_b32_e32 v163, 0xffff0000, v158
	v_lshlrev_b32_e32 v164, 16, v160
	v_lshlrev_b32_e32 v212, 16, v154
	v_and_b32_e32 v213, 0xffff0000, v154
	v_lshlrev_b32_e32 v154, 16, v155
	v_and_b32_e32 v155, 0xffff0000, v155
	v_lshlrev_b32_e32 v158, 16, v159
	v_and_b32_e32 v159, 0xffff0000, v159
	v_lshlrev_b32_e32 v160, 16, v161
	v_and_b32_e32 v161, 0xffff0000, v161
	v_lshlrev_b32_e32 v214, 16, v156
	v_and_b32_e32 v215, 0xffff0000, v156
	v_lshlrev_b32_e32 v156, 16, v157
	v_and_b32_e32 v157, 0xffff0000, v157
	v_ashrrev_i32_e32 v211, 31, v210
	s_lshl_b32 s6, s23, 1
	s_or_b32 s23, s42, 0x80
	s_waitcnt lgkmcnt(3)
	v_pk_fma_f32 v[162:163], v[168:169], v[162:163], v[166:167]
	s_waitcnt lgkmcnt(2)
	v_pk_fma_f32 v[154:155], v[172:173], v[154:155], v[170:171]
	s_waitcnt lgkmcnt(1)
	v_pk_fma_f32 v[164:165], v[176:177], v[164:165], v[174:175]
	v_pk_fma_f32 v[158:159], v[172:173], v[158:159], v[170:171]
	s_waitcnt lgkmcnt(0)
	v_pk_fma_f32 v[160:161], v[198:199], v[160:161], v[196:197]
	v_pk_fma_f32 v[166:167], v[168:169], v[212:213], v[166:167]
	v_pk_fma_f32 v[168:169], v[176:177], v[214:215], v[174:175]
	v_pk_fma_f32 v[156:157], v[198:199], v[156:157], v[196:197]
	v_pk_fma_f32 v[162:163], v[208:209], v[162:163], v[206:207] op_sel_hi:[0,1,0]
	v_pk_fma_f32 v[164:165], v[208:209], v[164:165], v[206:207] op_sel_hi:[0,1,0]
	v_pk_fma_f32 v[154:155], v[202:203], v[154:155], v[204:205] op_sel_hi:[0,1,0]
	v_pk_fma_f32 v[158:159], v[208:209], v[158:159], v[206:207] op_sel_hi:[0,1,0]
	v_pk_fma_f32 v[160:161], v[208:209], v[160:161], v[206:207] op_sel_hi:[0,1,0]
	v_pk_fma_f32 v[170:171], v[202:203], v[166:167], v[204:205] op_sel_hi:[0,1,0]
	v_pk_fma_f32 v[172:173], v[202:203], v[168:169], v[204:205] op_sel_hi:[0,1,0]
	v_pk_fma_f32 v[156:157], v[202:203], v[156:157], v[204:205] op_sel_hi:[0,1,0]
	v_cvt_pk_bf16_f32 v166, v162, v163
	v_cvt_pk_bf16_f32 v167, v158, v159
	v_cvt_pk_bf16_f32 v168, v164, v165
	v_cvt_pk_bf16_f32 v169, v160, v161
	v_cvt_pk_bf16_f32 v162, v170, v171
	v_cvt_pk_bf16_f32 v163, v154, v155
	v_cvt_pk_bf16_f32 v164, v172, v173
	v_cvt_pk_bf16_f32 v165, v156, v157
	global_load_dword v154, v[200:201], off
	v_lshlrev_b64 v[156:157], 8, v[210:211]
	v_lshl_add_u64 v[214:215], v[218:219], 0, v[156:157]
	global_load_dwordx4 v[158:161], v[214:215], off
	global_load_dwordx4 v[170:173], v[214:215], off offset:64
	global_load_dwordx4 v[174:177], v[214:215], off offset:128
	global_load_dwordx4 v[222:225], v[214:215], off offset:192
	v_pk_mul_f32 v[156:157], v[124:125], v[124:125]
	v_pk_mul_f32 v[212:213], v[122:123], v[122:123]
	v_mov_b64_e32 v[196:197], s[18:19]
	v_pk_fma_f32 v[116:117], v[212:213], s[16:17], v[196:197] op_sel_hi:[1,0,0] neg_lo:[1,0,0] neg_hi:[1,0,0]
	v_exp_f32_e32 v212, v226
	v_exp_f32_e32 v213, v227
	v_pk_fma_f32 v[156:157], v[156:157], s[16:17], v[196:197] op_sel_hi:[1,0,0] neg_lo:[1,0,0] neg_hi:[1,0,0]
	v_pk_fma_f32 v[226:227], v[228:229], s[16:17], v[196:197] op_sel_hi:[1,0,0] neg_lo:[1,0,0] neg_hi:[1,0,0]
	v_pk_fma_f32 v[128:129], v[128:129], s[16:17], v[196:197] op_sel_hi:[1,0,0] neg_lo:[1,0,0] neg_hi:[1,0,0]
	v_exp_f32_e32 v228, v230
	v_exp_f32_e32 v229, v231
	v_pk_mul_f32 v[116:117], v[122:123], v[116:117]
	v_pk_mul_f32 v[122:123], v[124:125], v[156:157]
	v_pk_mul_f32 v[118:119], v[118:119], v[226:227]
	v_pk_mul_f32 v[120:121], v[120:121], v[128:129]
	v_exp_f32_e32 v116, v116
	v_exp_f32_e32 v117, v117
	v_exp_f32_e32 v122, v122
	v_exp_f32_e32 v123, v123
	v_exp_f32_e32 v118, v118
	v_exp_f32_e32 v119, v119
	v_exp_f32_e32 v120, v120
	v_exp_f32_e32 v121, v121
	v_pk_add_f32 v[124:125], v[212:213], 1.0 op_sel_hi:[1,0]
	v_pk_add_f32 v[128:129], v[228:229], 1.0 op_sel_hi:[1,0]
	v_pk_fma_f32 v[124:125], v[116:117], v[124:125], v[124:125]
	v_pk_fma_f32 v[122:123], v[122:123], v[126:127], v[126:127]
	v_pk_fma_f32 v[126:127], v[118:119], v[128:129], v[128:129]
	v_pk_fma_f32 v[128:129], v[120:121], v[114:115], v[114:115]
	v_mov_b64_e32 v[198:199], s[56:57]
	v_rcp_f32_e32 v244, v122
	v_add_u32_e32 v122, s42, v210
	v_rcp_f32_e32 v245, v123
	v_mad_i64_i32 v[122:123], s[26:27], v122, s61, v[198:199]
	v_lshl_add_u64 v[122:123], v[122:123], 0, s[40:41]
	v_lshl_add_u64 v[122:123], v[122:123], 0, s[6:7]
	v_rcp_f32_e32 v242, v124
	v_rcp_f32_e32 v243, v125
	v_rcp_f32_e32 v246, v126
	v_rcp_f32_e32 v247, v127
	v_rcp_f32_e32 v248, v128
	v_rcp_f32_e32 v249, v129
	v_lshl_add_u64 v[250:251], v[122:123], 0, v[186:187]
	v_or_b32_e32 v212, 16, v210
	v_ashrrev_i32_e32 v213, 31, v212
	v_add_u32_e32 v211, s42, v212
	s_waitcnt vmcnt(4)
; #define GAS __attribute__((address_space(1)))
; __device__ __forceinline__ v4u pack8(const float (&f)[8]) { v4u w; w.x = pk2(f[0], f[1]); w.y = pk2(f[2], f[3]); w.z = pk2(f[4], f[5]); w.w = pk2(f[6], f[7]); return w; }
; __device__ __forceinline__ float fexp2(float x) { return __builtin_amdgcn_exp2f(x); }
; __device__ __forceinline__ float frcp(float x) { return __builtin_amdgcn_rcpf(x); }
;     __device__ __forceinline__ void operator()(const af4 (&acc)[2][2][4][2], const pg8::Unit& u, int wr_, int wc_, int fr_, int fq_) const {
;     ...
;             for (int m = 0; m < 4; ++m) {
;                 if (ai == 0 && m == 0) load_raw(1);
;                 const int it = wr * 64 + m * 16 + fr;
;                 bf16x8 wf[4];
; #pragma unroll
;                 for (int ks = 0; ks < 4; ++ks) wf[ks] = *(const GAS bf16x8*)(wsg + (size_t)it * 128 + 32 * ks + 8 * fq);
;                 const float bsi = bs[grp * 128 + it];
;                 af4 vm[2] = {(af4){bsi, bsi, bsi, bsi}, (af4){bsi, bsi, bsi, bsi}};
; #pragma unroll
;                 for (int ks = 0; ks < 4; ++ks) {
; #pragma unroll
;                     for (int n = 0; n < 2; ++n) vm[n] = __builtin_amdgcn_mfma_f32_16x16x32_bf16(av[n][ks], wf[ks], vm[n], 0, 0, 0);
;                 }
;                 float o[8];
; #pragma unroll
;                 for (int n = 0; n < 2; ++n)
; #pragma unroll
;                     for (int e = 0; e < 4; e += 2) {
;                         const f32x2 uu = {acc[ai][0][m][n][e], acc[ai][0][m][n][e + 1]}, gg = {acc[ai][1][m][n][e], acc[ai][1][m][n][e + 1]}, vv = {vm[n][e], vm[n][e + 1]};
;                         const f32x2 ar = uu * (uu * uu * (-2.302208198f * 0.044715f) + (-2.302208198f));
;                         const f32x2 gs = gg * (-1.4426950408889634f);
;                         const f32x2 ea = {fexp2(ar.x), fexp2(ar.y)}, eb = {fexp2(gs.x), fexp2(gs.y)};
;                         const f32x2 q = eb + 1.0f, den = ea * q + q;
;                         const f32x2 r = {frcp(den.x), frcp(den.y)};
;                         const f32x2 w = (uu * gg) * vv * r;
;                         o[4 * n + e] = w.x; o[4 * n + e + 1] = w.y; }
;                 *(GAS v4u*)(Y + (size_t)(tok0 + it) * CW + chbase + 32 * wc + 8 * fq) = pack8(o);
;             }
	v_mov_b32_e32 v155, v154
	v_mov_b32_e32 v156, v154
	v_mov_b32_e32 v157, v154
	s_waitcnt vmcnt(3)
	s_nop 0
	v_mfma_f32_16x16x32_bf16 v[114:117], v[130:133], v[158:161], v[154:157]
	v_mfma_f32_16x16x32_bf16 v[118:121], v[134:137], v[158:161], v[154:157]
	s_waitcnt vmcnt(2)
	v_mfma_f32_16x16x32_bf16 v[114:117], v[142:145], v[170:173], v[114:117]
	v_mfma_f32_16x16x32_bf16 v[118:121], v[138:141], v[170:173], v[118:121]
	s_waitcnt vmcnt(1)
	v_mfma_f32_16x16x32_bf16 v[114:117], v[150:153], v[174:177], v[114:117]
	v_mfma_f32_16x16x32_bf16 v[226:229], v[146:149], v[174:177], v[118:121]
	global_load_dwordx4 v[174:177], v[216:217], off offset:256
	global_load_dwordx4 v[158:161], v[216:217], off offset:320
	global_load_dwordx4 v[170:173], v[220:221], off offset:256
	global_load_dwordx4 v[154:157], v[220:221], off offset:320
	s_waitcnt vmcnt(4)
	v_mfma_f32_16x16x32_bf16 v[230:233], v[166:169], v[222:225], v[114:117]
	global_load_dwordx4 v[126:129], v[216:217], off offset:384
	global_load_dwordx4 v[118:121], v[216:217], off offset:448
	global_load_dwordx4 v[122:125], v[220:221], off offset:384
	global_load_dwordx4 v[114:117], v[220:221], off offset:448
	v_mfma_f32_16x16x32_bf16 v[220:223], v[162:165], v[222:225], v[226:229]
	s_nop 2
	v_mul_f32_e64 v216, v234, v230
	v_mul_f32_e64 v217, v235, v231
	v_pk_mul_f32 v[224:225], v[236:237], v[232:233]
	v_pk_mul_f32 v[216:217], v[242:243], v[216:217]
	v_pk_mul_f32 v[224:225], v[244:245], v[224:225]
	v_pk_mul_f32 v[242:243], v[110:111], s[20:21] op_sel_hi:[1,0]
	v_pk_mul_f32 v[220:221], v[238:239], v[220:221]
	v_pk_mul_f32 v[222:223], v[240:241], v[222:223]
	v_pk_mul_f32 v[226:227], v[246:247], v[220:221]
	v_pk_mul_f32 v[228:229], v[248:249], v[222:223]
	v_cvt_pk_bf16_f32 v220, v216, v217
	v_cvt_pk_bf16_f32 v221, v224, v225
	v_cvt_pk_bf16_f32 v222, v226, v227
	v_lshlrev_b64 v[216:217], 8, v[212:213]
	v_cvt_pk_bf16_f32 v223, v228, v229
	global_store_dwordx4 v[250:251], v[220:223], off
	s_nop 0
	v_lshl_add_u64 v[216:217], v[218:219], 0, v[216:217]
	ds_read_b128 v[224:227], v189 offset:0
	ds_read_b128 v[228:231], v189 offset:1024
	ds_read_b128 v[232:235], v189 offset:2048
	ds_read_b128 v[236:239], v189 offset:3072
	v_pk_mul_f32 v[222:223], v[108:109], v[108:109]
	v_pk_mul_f32 v[240:241], v[106:107], v[106:107]
	v_pk_mul_f32 v[244:245], v[112:113], s[20:21] op_sel_hi:[1,0]
	v_pk_mul_f32 v[248:249], v[102:103], v[102:103]
	v_pk_mul_f32 v[250:251], v[98:99], s[20:21] op_sel_hi:[1,0]
	v_pk_mul_f32 v[98:99], v[100:101], s[20:21] op_sel_hi:[1,0]
	v_pk_fma_f32 v[100:101], v[240:241], s[16:17], v[196:197] op_sel_hi:[1,0,0] neg_lo:[1,0,0] neg_hi:[1,0,0]
	v_pk_fma_f32 v[222:223], v[222:223], s[16:17], v[196:197] op_sel_hi:[1,0,0] neg_lo:[1,0,0] neg_hi:[1,0,0]
	v_exp_f32_e32 v240, v242
	v_exp_f32_e32 v241, v243
	v_exp_f32_e32 v242, v244
	v_exp_f32_e32 v243, v245
	v_pk_fma_f32 v[244:245], v[248:249], s[16:17], v[196:197] op_sel_hi:[1,0,0] neg_lo:[1,0,0] neg_hi:[1,0,0]
	v_exp_f32_e32 v248, v250
	v_exp_f32_e32 v249, v251
	v_exp_f32_e32 v250, v98
	v_exp_f32_e32 v251, v99
	v_pk_mul_f32 v[98:99], v[106:107], v[100:101]
	v_pk_mul_f32 v[100:101], v[108:109], v[222:223]
	v_pk_mul_f32 v[110:111], v[106:107], v[110:111]
	v_pk_mul_f32 v[112:113], v[108:109], v[112:113]
	v_pk_mul_f32 v[246:247], v[104:105], v[104:105]
	v_exp_f32_e32 v106, v98
	v_exp_f32_e32 v107, v99
	v_exp_f32_e32 v108, v100
	v_exp_f32_e32 v109, v101
	v_pk_fma_f32 v[246:247], v[246:247], s[16:17], v[196:197] op_sel_hi:[1,0,0] neg_lo:[1,0,0] neg_hi:[1,0,0]
	v_pk_mul_f32 v[102:103], v[102:103], v[244:245]
	v_pk_mul_f32 v[104:105], v[104:105], v[246:247]
	v_exp_f32_e32 v244, v102
	v_exp_f32_e32 v245, v103
	v_exp_f32_e32 v246, v104
	v_exp_f32_e32 v247, v105
	v_pk_add_f32 v[102:103], v[240:241], 1.0 op_sel_hi:[1,0]
	v_pk_add_f32 v[104:105], v[242:243], 1.0 op_sel_hi:[1,0]
	v_pk_fma_f32 v[106:107], v[106:107], v[102:103], v[102:103]
	v_pk_fma_f32 v[108:109], v[108:109], v[104:105], v[104:105]
	v_pk_add_f32 v[240:241], v[248:249], 1.0 op_sel_hi:[1,0]
	v_pk_add_f32 v[242:243], v[250:251], 1.0 op_sel_hi:[1,0]
	v_mov_b32_e32 v220, v179
	v_mov_b32_e32 v221, v220
	v_mov_b32_e32 v222, v220
	v_mov_b32_e32 v223, v220
	s_waitcnt lgkmcnt(3)
	s_nop 0
	v_mfma_f32_16x16x32_bf16 v[98:101], v[130:133], v[224:227], v[220:223]
	v_mfma_f32_16x16x32_bf16 v[102:105], v[134:137], v[224:227], v[220:223]
	v_rcp_f32_e32 v224, v106
	v_rcp_f32_e32 v225, v107
	v_rcp_f32_e32 v226, v108
	s_waitcnt lgkmcnt(2)
	v_mfma_f32_16x16x32_bf16 v[98:101], v[142:145], v[228:231], v[98:101]
	v_rcp_f32_e32 v227, v109
	v_pk_fma_f32 v[220:221], v[244:245], v[240:241], v[240:241]
	v_pk_fma_f32 v[222:223], v[246:247], v[242:243], v[242:243]
	v_mfma_f32_16x16x32_bf16 v[102:105], v[138:141], v[228:231], v[102:105]
	v_rcp_f32_e32 v220, v220
	v_rcp_f32_e32 v221, v221
	v_rcp_f32_e32 v222, v222
	s_waitcnt lgkmcnt(1)
	v_mfma_f32_16x16x32_bf16 v[106:109], v[150:153], v[232:235], v[98:101]
	v_rcp_f32_e32 v223, v223
	v_mad_i64_i32 v[228:229], s[26:27], v211, s61, v[198:199]
	v_mfma_f32_16x16x32_bf16 v[100:103], v[146:149], v[232:235], v[102:105]
	v_or_b32_e32 v98, 32, v210
	v_ashrrev_i32_e32 v99, 31, v98
	v_pk_mul_f32 v[234:235], v[86:87], v[86:87]
	s_waitcnt lgkmcnt(0)
; #define GAS __attribute__((address_space(1)))
; __device__ __forceinline__ v4u pack8(const float (&f)[8]) { v4u w; w.x = pk2(f[0], f[1]); w.y = pk2(f[2], f[3]); w.z = pk2(f[4], f[5]); w.w = pk2(f[6], f[7]); return w; }
; __device__ __forceinline__ float fexp2(float x) { return __builtin_amdgcn_exp2f(x); }
; __device__ __forceinline__ float frcp(float x) { return __builtin_amdgcn_rcpf(x); }
;     __device__ __forceinline__ void operator()(const af4 (&acc)[2][2][4][2], const pg8::Unit& u, int wr_, int wc_, int fr_, int fq_) const {
;     ...
;             for (int m = 0; m < 4; ++m) {
;                 if (ai == 0 && m == 0) load_raw(1);
;                 const int it = wr * 64 + m * 16 + fr;
;                 bf16x8 wf[4];
; #pragma unroll
;                 for (int ks = 0; ks < 4; ++ks) wf[ks] = *(const GAS bf16x8*)(wsg + (size_t)it * 128 + 32 * ks + 8 * fq);
;                 const float bsi = bs[grp * 128 + it];
;                 af4 vm[2] = {(af4){bsi, bsi, bsi, bsi}, (af4){bsi, bsi, bsi, bsi}};
; #pragma unroll
;                 for (int ks = 0; ks < 4; ++ks) {
; #pragma unroll
;                     for (int n = 0; n < 2; ++n) vm[n] = __builtin_amdgcn_mfma_f32_16x16x32_bf16(av[n][ks], wf[ks], vm[n], 0, 0, 0);
;                 }
;                 float o[8];
; #pragma unroll
;                 for (int n = 0; n < 2; ++n)
; #pragma unroll
;                     for (int e = 0; e < 4; e += 2) {
;                         const f32x2 uu = {acc[ai][0][m][n][e], acc[ai][0][m][n][e + 1]}, gg = {acc[ai][1][m][n][e], acc[ai][1][m][n][e + 1]}, vv = {vm[n][e], vm[n][e + 1]};
;                         const f32x2 ar = uu * (uu * uu * (-2.302208198f * 0.044715f) + (-2.302208198f));
;                         const f32x2 gs = gg * (-1.4426950408889634f);
;                         const f32x2 ea = {fexp2(ar.x), fexp2(ar.y)}, eb = {fexp2(gs.x), fexp2(gs.y)};
;                         const f32x2 q = eb + 1.0f, den = ea * q + q;
;                         const f32x2 r = {frcp(den.x), frcp(den.y)};
;                         const f32x2 w = (uu * gg) * vv * r;
;                         o[4 * n + e] = w.x; o[4 * n + e + 1] = w.y; }
;                 *(GAS v4u*)(Y + (size_t)(tok0 + it) * CW + chbase + 32 * wc + 8 * fq) = pack8(o);
;             }
	v_mfma_f32_16x16x32_bf16 v[104:107], v[166:169], v[236:239], v[106:109]
	v_mul_f32_e64 v240, v88, v84
	v_mul_f32_e64 v241, v89, v85
	v_pk_mul_f32 v[232:233], v[88:89], v[88:89]
	v_mfma_f32_16x16x32_bf16 v[100:103], v[162:165], v[236:239], v[100:103]
	v_lshl_add_u64 v[108:109], v[228:229], 0, s[40:41]
	v_lshl_add_u64 v[108:109], v[108:109], 0, s[6:7]
	v_lshl_add_u64 v[108:109], v[108:109], 0, v[186:187]
	s_nop 0
	v_pk_mul_f32 v[104:105], v[110:111], v[104:105]
	v_pk_mul_f32 v[106:107], v[112:113], v[106:107]
	s_nop 1
	v_pk_mul_f32 v[100:101], v[252:253], v[100:101]
	v_pk_mul_f32 v[102:103], v[192:193], v[102:103]
	v_pk_mul_f32 v[104:105], v[224:225], v[104:105]
	v_pk_mul_f32 v[106:107], v[226:227], v[106:107]
	v_pk_mul_f32 v[110:111], v[220:221], v[100:101]
	v_pk_mul_f32 v[112:113], v[222:223], v[102:103]
	v_cvt_pk_bf16_f32 v100, v104, v105
	v_cvt_pk_bf16_f32 v101, v106, v107
	v_cvt_pk_bf16_f32 v102, v110, v111
	v_pk_mul_f32 v[106:107], v[90:91], v[90:91]
	v_cvt_pk_bf16_f32 v103, v112, v113
	global_store_dwordx4 v[108:109], v[100:103], off
	s_nop 0
	v_pk_mul_f32 v[112:113], v[94:95], s[20:21] op_sel_hi:[1,0]
	v_lshlrev_b64 v[100:101], 8, v[98:99]
	v_lshl_add_u64 v[102:103], v[218:219], 0, v[100:101]
	ds_read_b128 v[108:111], v189 offset:4096
	ds_read_b128 v[220:223], v189 offset:5120
	ds_read_b128 v[224:227], v189 offset:6144
	ds_read_b128 v[228:231], v189 offset:7168
	v_pk_mul_f32 v[100:101], v[92:93], v[92:93]
	v_pk_mul_f32 v[192:193], v[96:97], s[20:21] op_sel_hi:[1,0]
	v_pk_mul_f32 v[236:237], v[82:83], s[20:21] op_sel_hi:[1,0]
	v_pk_mul_f32 v[238:239], v[86:87], v[82:83]
	v_pk_mul_f32 v[82:83], v[84:85], s[20:21] op_sel_hi:[1,0]
	v_pk_fma_f32 v[84:85], v[106:107], s[16:17], v[196:197] op_sel_hi:[1,0,0] neg_lo:[1,0,0] neg_hi:[1,0,0]
	v_exp_f32_e32 v106, v112
	v_exp_f32_e32 v107, v113
	v_pk_fma_f32 v[100:101], v[100:101], s[16:17], v[196:197] op_sel_hi:[1,0,0] neg_lo:[1,0,0] neg_hi:[1,0,0]
	v_exp_f32_e32 v112, v192
	v_exp_f32_e32 v113, v193
	v_pk_fma_f32 v[192:193], v[234:235], s[16:17], v[196:197] op_sel_hi:[1,0,0] neg_lo:[1,0,0] neg_hi:[1,0,0]
	v_exp_f32_e32 v234, v236
	v_exp_f32_e32 v235, v237
	v_exp_f32_e32 v236, v82
	v_exp_f32_e32 v237, v83
	v_pk_mul_f32 v[82:83], v[90:91], v[84:85]
	v_pk_mul_f32 v[84:85], v[92:93], v[100:101]
	v_pk_mul_f32 v[94:95], v[90:91], v[94:95]
	v_pk_mul_f32 v[96:97], v[92:93], v[96:97]
	v_exp_f32_e32 v90, v82
	v_exp_f32_e32 v91, v83
	v_exp_f32_e32 v92, v84
	v_exp_f32_e32 v93, v85
	v_pk_fma_f32 v[232:233], v[232:233], s[16:17], v[196:197] op_sel_hi:[1,0,0] neg_lo:[1,0,0] neg_hi:[1,0,0]
	v_pk_mul_f32 v[86:87], v[86:87], v[192:193]
	v_pk_mul_f32 v[88:89], v[88:89], v[232:233]
	v_exp_f32_e32 v100, v86
	v_exp_f32_e32 v101, v87
	v_pk_add_f32 v[86:87], v[106:107], 1.0 op_sel_hi:[1,0]
	v_exp_f32_e32 v192, v88
	v_exp_f32_e32 v193, v89
	v_pk_add_f32 v[88:89], v[112:113], 1.0 op_sel_hi:[1,0]
	v_pk_fma_f32 v[90:91], v[90:91], v[86:87], v[86:87]
	v_pk_fma_f32 v[92:93], v[92:93], v[88:89], v[88:89]
	v_pk_add_f32 v[112:113], v[234:235], 1.0 op_sel_hi:[1,0]
	v_pk_add_f32 v[232:233], v[236:237], 1.0 op_sel_hi:[1,0]
	v_pk_fma_f32 v[100:101], v[100:101], v[112:113], v[112:113]
	v_rcp_f32_e32 v90, v90
	v_rcp_f32_e32 v91, v91
	v_rcp_f32_e32 v92, v92
	v_rcp_f32_e32 v93, v93
	v_add_u32_e32 v99, s42, v98
	v_pk_mul_f32 v[112:113], v[78:79], s[20:21] op_sel_hi:[1,0]
	v_pk_mul_f32 v[78:79], v[74:75], v[78:79]
	v_mov_b32_e32 v104, v181
	v_mov_b32_e32 v105, v104
	v_mov_b32_e32 v106, v104
	v_mov_b32_e32 v107, v104
	s_waitcnt lgkmcnt(3)
	s_nop 0
	v_mfma_f32_16x16x32_bf16 v[82:85], v[130:133], v[108:111], v[104:107]
	v_mfma_f32_16x16x32_bf16 v[86:89], v[134:137], v[108:111], v[104:107]
	v_mad_i64_i32 v[108:109], s[26:27], v99, s61, v[198:199]
	v_lshl_add_u64 v[108:109], v[108:109], 0, s[40:41]
	s_waitcnt lgkmcnt(2)
	v_mfma_f32_16x16x32_bf16 v[82:85], v[142:145], v[220:223], v[82:85]
	v_fma_f32 v104, v192, v232, v232
	v_fma_f32 v105, v193, v233, v233
	v_rcp_f32_e32 v106, v100
	v_rcp_f32_e32 v107, v101
	v_mfma_f32_16x16x32_bf16 v[86:89], v[138:141], v[220:223], v[86:89]
	v_rcp_f32_e32 v104, v104
	v_rcp_f32_e32 v105, v105
	v_lshl_add_u64 v[108:109], v[108:109], 0, s[6:7]
	s_waitcnt lgkmcnt(1)
	v_mfma_f32_16x16x32_bf16 v[82:85], v[150:153], v[224:227], v[82:85]
	v_lshl_add_u64 v[108:109], v[108:109], 0, v[186:187]
	v_or_b32_e32 v100, 48, v210
	v_ashrrev_i32_e32 v101, 31, v100
	v_mfma_f32_16x16x32_bf16 v[86:89], v[146:149], v[224:227], v[86:89]
	v_mul_f32_e64 v110, v74, v74
	v_mul_f32_e64 v111, v75, v75
	v_pk_mul_f32 v[192:193], v[80:81], s[20:21] op_sel_hi:[1,0]
	v_pk_mul_f32 v[220:221], v[70:71], v[70:71]
	s_waitcnt lgkmcnt(0)
; #define GAS __attribute__((address_space(1)))
; __device__ __forceinline__ v4u pack8(const float (&f)[8]) { v4u w; w.x = pk2(f[0], f[1]); w.y = pk2(f[2], f[3]); w.z = pk2(f[4], f[5]); w.w = pk2(f[6], f[7]); return w; }
; __device__ __forceinline__ float fexp2(float x) { return __builtin_amdgcn_exp2f(x); }
; __device__ __forceinline__ float frcp(float x) { return __builtin_amdgcn_rcpf(x); }
;     __device__ __forceinline__ void operator()(const af4 (&acc)[2][2][4][2], const pg8::Unit& u, int wr_, int wc_, int fr_, int fq_) const {
;     ...
;             for (int m = 0; m < 4; ++m) {
;                 if (ai == 0 && m == 0) load_raw(1);
;                 const int it = wr * 64 + m * 16 + fr;
;                 bf16x8 wf[4];
; #pragma unroll
;                 for (int ks = 0; ks < 4; ++ks) wf[ks] = *(const GAS bf16x8*)(wsg + (size_t)it * 128 + 32 * ks + 8 * fq);
;                 const float bsi = bs[grp * 128 + it];
;                 af4 vm[2] = {(af4){bsi, bsi, bsi, bsi}, (af4){bsi, bsi, bsi, bsi}};
; #pragma unroll
;                 for (int ks = 0; ks < 4; ++ks) {
; #pragma unroll
;                     for (int n = 0; n < 2; ++n) vm[n] = __builtin_amdgcn_mfma_f32_16x16x32_bf16(av[n][ks], wf[ks], vm[n], 0, 0, 0);
;                 }
;                 float o[8];
; #pragma unroll
;                 for (int n = 0; n < 2; ++n)
; #pragma unroll
;                     for (int e = 0; e < 4; e += 2) {
;                         const f32x2 uu = {acc[ai][0][m][n][e], acc[ai][0][m][n][e + 1]}, gg = {acc[ai][1][m][n][e], acc[ai][1][m][n][e + 1]}, vv = {vm[n][e], vm[n][e + 1]};
;                         const f32x2 ar = uu * (uu * uu * (-2.302208198f * 0.044715f) + (-2.302208198f));
;                         const f32x2 gs = gg * (-1.4426950408889634f);
;                         const f32x2 ea = {fexp2(ar.x), fexp2(ar.y)}, eb = {fexp2(gs.x), fexp2(gs.y)};
;                         const f32x2 q = eb + 1.0f, den = ea * q + q;
;                         const f32x2 r = {frcp(den.x), frcp(den.y)};
;                         const f32x2 w = (uu * gg) * vv * r;
;                         o[4 * n + e] = w.x; o[4 * n + e + 1] = w.y; }
;                 *(GAS v4u*)(Y + (size_t)(tok0 + it) * CW + chbase + 32 * wc + 8 * fq) = pack8(o);
;             }
	v_mfma_f32_16x16x32_bf16 v[82:85], v[166:169], v[228:231], v[82:85]
	v_mul_f32_e64 v222, v66, s20
	v_mul_f32_e64 v223, v67, s20
	v_pk_mul_f32 v[224:225], v[70:71], v[66:67]
	v_pk_mul_f32 v[66:67], v[68:69], s[20:21] op_sel_hi:[1,0]
	v_mfma_f32_16x16x32_bf16 v[86:89], v[162:165], v[228:231], v[86:89]
	v_mul_f32_e64 v226, v72, v68
	v_mul_f32_e64 v227, v73, v69
	s_nop 0
	v_pk_mul_f32 v[82:83], v[94:95], v[82:83]
	v_pk_mul_f32 v[84:85], v[96:97], v[84:85]
	v_pk_mul_f32 v[82:83], v[90:91], v[82:83]
	v_pk_mul_f32 v[84:85], v[92:93], v[84:85]
	s_nop 0
	v_pk_mul_f32 v[86:87], v[238:239], v[86:87]
	v_pk_mul_f32 v[88:89], v[240:241], v[88:89]
	v_pk_mul_f32 v[86:87], v[106:107], v[86:87]
	v_pk_mul_f32 v[88:89], v[104:105], v[88:89]
	v_cvt_pk_bf16_f32 v82, v82, v83
	v_cvt_pk_bf16_f32 v83, v84, v85
	v_cvt_pk_bf16_f32 v84, v86, v87
	v_pk_fma_f32 v[68:69], v[110:111], s[16:17], v[196:197] op_sel_hi:[1,0,0] neg_lo:[1,0,0] neg_hi:[1,0,0]
	v_cvt_pk_bf16_f32 v85, v88, v89
	global_store_dwordx4 v[108:109], v[82:85], off
	s_nop 0
	v_exp_f32_e32 v110, v112
	v_lshlrev_b64 v[84:85], 8, v[100:101]
	v_lshl_add_u64 v[104:105], v[218:219], 0, v[84:85]
	ds_read_b128 v[86:89], v189 offset:8192
	ds_read_b128 v[90:93], v189 offset:9216
	ds_read_b128 v[94:97], v189 offset:10240
	ds_read_b128 v[106:109], v189 offset:11264
	v_pk_mul_f32 v[84:85], v[76:77], v[76:77]
	v_pk_mul_f32 v[218:219], v[72:73], v[72:73]
	v_exp_f32_e32 v111, v113
	v_pk_fma_f32 v[84:85], v[84:85], s[16:17], v[196:197] op_sel_hi:[1,0,0] neg_lo:[1,0,0] neg_hi:[1,0,0]
	v_exp_f32_e32 v112, v192
	v_exp_f32_e32 v113, v193
	v_pk_fma_f32 v[192:193], v[220:221], s[16:17], v[196:197] op_sel_hi:[1,0,0] neg_lo:[1,0,0] neg_hi:[1,0,0]
	v_pk_fma_f32 v[218:219], v[218:219], s[16:17], v[196:197] op_sel_hi:[1,0,0] neg_lo:[1,0,0] neg_hi:[1,0,0]
	v_pk_mul_f32 v[68:69], v[74:75], v[68:69]
	v_exp_f32_e32 v220, v222
	v_exp_f32_e32 v221, v223
	v_exp_f32_e32 v66, v66
	v_exp_f32_e32 v67, v67
	v_pk_mul_f32 v[74:75], v[76:77], v[84:85]
	v_pk_mul_f32 v[70:71], v[70:71], v[192:193]
	v_pk_mul_f32 v[72:73], v[72:73], v[218:219]
	v_exp_f32_e32 v68, v68
	v_exp_f32_e32 v69, v69
	v_exp_f32_e32 v74, v74
	v_exp_f32_e32 v75, v75
	v_exp_f32_e32 v70, v70
	v_exp_f32_e32 v71, v71
	v_exp_f32_e32 v72, v72
	v_exp_f32_e32 v73, v73
	v_pk_mul_f32 v[80:81], v[76:77], v[80:81]
	v_pk_add_f32 v[76:77], v[110:111], 1.0 op_sel_hi:[1,0]
	v_pk_add_f32 v[110:111], v[112:113], 1.0 op_sel_hi:[1,0]
	v_pk_add_f32 v[112:113], v[220:221], 1.0 op_sel_hi:[1,0]
	v_pk_add_f32 v[192:193], v[66:67], 1.0 op_sel_hi:[1,0]
	v_pk_fma_f32 v[76:77], v[68:69], v[76:77], v[76:77]
	v_pk_fma_f32 v[74:75], v[74:75], v[110:111], v[110:111]
	v_pk_fma_f32 v[110:111], v[70:71], v[112:113], v[112:113]
	v_pk_fma_f32 v[112:113], v[72:73], v[192:193], v[192:193]
	v_rcp_f32_e32 v76, v76
	v_rcp_f32_e32 v77, v77
	v_rcp_f32_e32 v74, v74
	v_rcp_f32_e32 v75, v75
	v_add_u32_e32 v99, s23, v210
	s_waitcnt vmcnt(3)
	v_mov_b32_e32 v82, v183
	v_mov_b32_e32 v83, v82
	v_mov_b32_e32 v84, v82
	v_mov_b32_e32 v85, v82
	s_waitcnt lgkmcnt(3)
	s_nop 0
	v_mfma_f32_16x16x32_bf16 v[66:69], v[130:133], v[86:89], v[82:85]
	v_lshlrev_b32_e32 v130, 16, v156
	v_and_b32_e32 v131, 0xffff0000, v156
	v_lshlrev_b32_e32 v132, 16, v157
	v_mfma_f32_16x16x32_bf16 v[70:73], v[134:137], v[86:89], v[82:85]
	v_rcp_f32_e32 v86, v112
	v_rcp_f32_e32 v87, v113
	v_lshlrev_b32_e32 v112, 16, v155
	s_waitcnt lgkmcnt(2)
	v_mfma_f32_16x16x32_bf16 v[66:69], v[142:145], v[90:93], v[66:69]
	v_rcp_f32_e32 v84, v110
	v_rcp_f32_e32 v85, v111
	v_or_b32_e32 v82, s23, v209
	v_mfma_f32_16x16x32_bf16 v[70:73], v[138:141], v[90:93], v[70:73]
	v_add_u32_e32 v90, s42, v100
	v_mad_i64_i32 v[90:91], s[26:27], v90, s61, v[198:199]
	s_waitcnt lgkmcnt(1)
	v_mfma_f32_16x16x32_bf16 v[66:69], v[150:153], v[94:97], v[66:69]
	v_lshl_add_u64 v[90:91], v[90:91], 0, s[40:41]
	v_lshl_add_u64 v[90:91], v[90:91], 0, s[6:7]
	v_ashrrev_i32_e32 v83, 31, v82
	v_mfma_f32_16x16x32_bf16 v[70:73], v[146:149], v[94:97], v[70:73]
	v_lshl_add_u64 v[90:91], v[90:91], 0, v[186:187]
	v_lshl_add_u32 v88, v82, 3, s98
	v_lshlrev_b32_e32 v92, 16, v177
	s_waitcnt lgkmcnt(0)
	v_mfma_f32_16x16x32_bf16 v[66:69], v[166:169], v[106:109], v[66:69]
	v_and_b32_e32 v93, 0xffff0000, v177
	v_lshlrev_b32_e32 v94, 16, v170
	v_and_b32_e32 v95, 0xffff0000, v170
	v_mfma_f32_16x16x32_bf16 v[70:73], v[162:165], v[106:109], v[70:73]
	v_lshlrev_b32_e32 v96, 16, v171
	s_nop 2
	v_pk_mul_f32 v[66:67], v[78:79], v[66:67]
	v_pk_mul_f32 v[68:69], v[80:81], v[68:69]
	v_pk_mul_f32 v[66:67], v[76:77], v[66:67]
	v_pk_mul_f32 v[68:69], v[74:75], v[68:69]
	v_pk_mul_f32 v[70:71], v[224:225], v[70:71]
	v_pk_mul_f32 v[72:73], v[226:227], v[72:73]
	v_pk_mul_f32 v[70:71], v[84:85], v[70:71]
	v_pk_mul_f32 v[72:73], v[86:87], v[72:73]
	v_cvt_pk_bf16_f32 v66, v66, v67
	v_cvt_pk_bf16_f32 v67, v68, v69
	v_cvt_pk_bf16_f32 v68, v70, v71
	v_or_b32_e32 v84, 32, v82
	v_cvt_pk_bf16_f32 v69, v72, v73
	global_store_dwordx4 v[90:91], v[66:69], off
	global_load_dword v250, v[200:201], off
	global_load_dwordx4 v[234:237], v[214:215], off
	global_load_dwordx4 v[238:241], v[214:215], off offset:64
	global_load_dwordx4 v[242:245], v[214:215], off offset:128
	global_load_dwordx4 v[246:249], v[214:215], off offset:192
	ds_read_b128 v[66:69], v88
	s_nop 0
	ds_read_b128 v[70:73], v88 offset:16
	ds_read_b128 v[74:77], v88 offset:32
	ds_read_b128 v[78:81], v88 offset:48
	v_ashrrev_i32_e32 v85, 31, v84
	v_lshl_add_u32 v88, v84, 3, s98
	v_lshlrev_b32_e32 v84, 16, v174
	v_and_b32_e32 v85, 0xffff0000, v174
	v_lshlrev_b32_e32 v86, 16, v175
	v_and_b32_e32 v87, 0xffff0000, v175
	v_lshlrev_b32_e32 v90, 16, v176
	v_and_b32_e32 v91, 0xffff0000, v176
	v_and_b32_e32 v97, 0xffff0000, v171
	v_lshlrev_b32_e32 v106, 16, v172
	v_and_b32_e32 v107, 0xffff0000, v172
	v_lshlrev_b32_e32 v108, 16, v173
	v_and_b32_e32 v109, 0xffff0000, v173
	v_lshlrev_b32_e32 v110, 16, v154
	v_and_b32_e32 v111, 0xffff0000, v154
	v_and_b32_e32 v113, 0xffff0000, v155
	v_and_b32_e32 v133, 0xffff0000, v157
	v_pk_mul_f32 v[134:135], v[54:55], v[54:55]
	v_pk_mul_f32 v[136:137], v[50:51], s[20:21] op_sel_hi:[1,0]
	v_pk_mul_f32 v[138:139], v[54:55], v[50:51]
	v_pk_mul_f32 v[50:51], v[52:53], s[20:21] op_sel_hi:[1,0]
	v_pk_mul_f32 v[140:141], v[56:57], v[52:53]
	s_waitcnt lgkmcnt(3)
; #define GAS __attribute__((address_space(1)))
; __device__ __forceinline__ void unpack8(const v4u w, float (&f)[8]) { f[0] = bflo(w.x); f[1] = bfhi(w.x); f[2] = bflo(w.y); f[3] = bfhi(w.y); f[4] = bflo(w.z); f[5] = bfhi(w.z); f[6] = bflo(w.w); f[7] = bfhi(w.w); }
; __device__ __forceinline__ v4u pack8(const float (&f)[8]) { v4u w; w.x = pk2(f[0], f[1]); w.y = pk2(f[2], f[3]); w.z = pk2(f[4], f[5]); w.w = pk2(f[6], f[7]); return w; }
;     __device__ __forceinline__ void operator()(const af4 (&acc)[2][2][4][2], const pg8::Unit& u, int wr_, int wc_, int fr_, int fq_) const {
;     ...
;             for (int ks = 0; ks < 4; ++ks) {
;                 const int j0 = tok0 + 32 * ks + 8 * fq;
;                 f32x4 st[4];
; #pragma unroll
;                 for (int q = 0; q < 4; ++q) st[q] = *(const GAS f32x4*)(stats + (size_t)(j0 + 2 * q) * 2);
; #pragma unroll
;                 for (int n = 0; n < 2; ++n) {
;                     float vf[8];
;                     unpack8(raw[n][ks], vf);
; #pragma unroll
;                     for (int q = 0; q < 4; ++q) { f32x2 t = {vf[2 * q], vf[2 * q + 1]}; t = t * (f32x2){st[q].z, st[q].w} + (f32x2){st[q].x, st[q].y}; t = t * lg[n] + lb[n]; vf[2 * q] = t.x; vf[2 * q + 1] = t.y; }
;                     av[n][ks] = __builtin_bit_cast(bf16x8, pack8(vf));
;                 }
;             }
	v_pk_fma_f32 v[84:85], v[68:69], v[84:85], v[66:67]
	s_waitcnt lgkmcnt(2)
	v_pk_fma_f32 v[86:87], v[72:73], v[86:87], v[70:71]
	s_waitcnt lgkmcnt(1)
	v_pk_fma_f32 v[90:91], v[76:77], v[90:91], v[74:75]
	s_waitcnt lgkmcnt(0)
	v_pk_fma_f32 v[92:93], v[80:81], v[92:93], v[78:79]
	v_pk_fma_f32 v[66:67], v[68:69], v[94:95], v[66:67]
	v_pk_fma_f32 v[68:69], v[72:73], v[96:97], v[70:71]
	v_pk_fma_f32 v[70:71], v[76:77], v[106:107], v[74:75]
	v_pk_fma_f32 v[72:73], v[80:81], v[108:109], v[78:79]
	v_pk_fma_f32 v[74:75], v[208:209], v[84:85], v[206:207] op_sel_hi:[0,1,0]
	v_pk_fma_f32 v[76:77], v[208:209], v[86:87], v[206:207] op_sel_hi:[0,1,0]
	v_pk_fma_f32 v[78:79], v[208:209], v[90:91], v[206:207] op_sel_hi:[0,1,0]
	v_pk_fma_f32 v[80:81], v[208:209], v[92:93], v[206:207] op_sel_hi:[0,1,0]
	v_pk_fma_f32 v[66:67], v[202:203], v[66:67], v[204:205] op_sel_hi:[0,1,0]
	v_pk_fma_f32 v[68:69], v[202:203], v[68:69], v[204:205] op_sel_hi:[0,1,0]
	v_pk_fma_f32 v[84:85], v[202:203], v[70:71], v[204:205] op_sel_hi:[0,1,0]
	v_pk_fma_f32 v[86:87], v[202:203], v[72:73], v[204:205] op_sel_hi:[0,1,0]
	v_cvt_pk_bf16_f32 v70, v74, v75
	v_cvt_pk_bf16_f32 v71, v76, v77
	v_cvt_pk_bf16_f32 v72, v78, v79
	v_cvt_pk_bf16_f32 v73, v80, v81
	v_cvt_pk_bf16_f32 v66, v66, v67
	v_cvt_pk_bf16_f32 v67, v68, v69
	v_cvt_pk_bf16_f32 v68, v84, v85
	v_cvt_pk_bf16_f32 v69, v86, v87
	ds_read_b128 v[74:77], v88
	ds_read_b128 v[78:81], v88 offset:16
	ds_read_b128 v[84:87], v88 offset:32
	s_nop 0
	ds_read_b128 v[88:91], v88 offset:48
	v_or_b32_e32 v92, 64, v82
	v_ashrrev_i32_e32 v93, 31, v92
	v_lshl_add_u32 v96, v92, 3, s98
	v_lshlrev_b32_e32 v92, 16, v158
	v_and_b32_e32 v93, 0xffff0000, v158
	v_lshlrev_b32_e32 v94, 16, v159
	v_and_b32_e32 v95, 0xffff0000, v159
	v_lshlrev_b32_e32 v106, 16, v160
	v_and_b32_e32 v107, 0xffff0000, v160
	v_lshlrev_b32_e32 v108, 16, v161
	v_and_b32_e32 v109, 0xffff0000, v161
	v_or_b32_e32 v82, 0x60, v82
	v_ashrrev_i32_e32 v83, 31, v82
	s_waitcnt lgkmcnt(3)
	v_pk_fma_f32 v[92:93], v[76:77], v[92:93], v[74:75]
	s_waitcnt lgkmcnt(2)
	v_pk_fma_f32 v[94:95], v[80:81], v[94:95], v[78:79]
	s_waitcnt lgkmcnt(1)
	v_pk_fma_f32 v[106:107], v[86:87], v[106:107], v[84:85]
	s_waitcnt lgkmcnt(0)
	v_pk_fma_f32 v[108:109], v[90:91], v[108:109], v[88:89]
	v_pk_fma_f32 v[74:75], v[76:77], v[110:111], v[74:75]
	v_pk_fma_f32 v[76:77], v[80:81], v[112:113], v[78:79]
	v_pk_fma_f32 v[78:79], v[86:87], v[130:131], v[84:85]
	v_pk_fma_f32 v[80:81], v[90:91], v[132:133], v[88:89]
	v_pk_fma_f32 v[84:85], v[208:209], v[92:93], v[206:207] op_sel_hi:[0,1,0]
	v_pk_fma_f32 v[86:87], v[208:209], v[94:95], v[206:207] op_sel_hi:[0,1,0]
	v_pk_fma_f32 v[88:89], v[208:209], v[106:107], v[206:207] op_sel_hi:[0,1,0]
	v_pk_fma_f32 v[90:91], v[208:209], v[108:109], v[206:207] op_sel_hi:[0,1,0]
	v_pk_fma_f32 v[74:75], v[202:203], v[74:75], v[204:205] op_sel_hi:[0,1,0]
	v_pk_fma_f32 v[76:77], v[202:203], v[76:77], v[204:205] op_sel_hi:[0,1,0]
	v_pk_fma_f32 v[92:93], v[202:203], v[78:79], v[204:205] op_sel_hi:[0,1,0]
	v_pk_fma_f32 v[94:95], v[202:203], v[80:81], v[204:205] op_sel_hi:[0,1,0]
	v_cvt_pk_bf16_f32 v78, v84, v85
	v_cvt_pk_bf16_f32 v79, v86, v87
	v_cvt_pk_bf16_f32 v80, v88, v89
	v_cvt_pk_bf16_f32 v81, v90, v91
	v_cvt_pk_bf16_f32 v74, v74, v75
	v_cvt_pk_bf16_f32 v75, v76, v77
	v_cvt_pk_bf16_f32 v76, v92, v93
	v_cvt_pk_bf16_f32 v77, v94, v95
	ds_read_b128 v[84:87], v96
	ds_read_b128 v[88:91], v96 offset:16
	ds_read_b128 v[92:95], v96 offset:32
	ds_read_b128 v[106:109], v96 offset:48
	v_lshl_add_u32 v110, v82, 3, s98
	v_lshlrev_b32_e32 v82, 16, v126
	v_and_b32_e32 v83, 0xffff0000, v126
	v_lshlrev_b32_e32 v96, 16, v127
	v_and_b32_e32 v97, 0xffff0000, v127
	v_lshlrev_b32_e32 v112, 16, v128
	v_and_b32_e32 v113, 0xffff0000, v128
	v_lshlrev_b32_e32 v126, 16, v129
	v_and_b32_e32 v127, 0xffff0000, v129
	v_lshlrev_b32_e32 v128, 16, v122
	v_and_b32_e32 v129, 0xffff0000, v122
	v_lshlrev_b32_e32 v122, 16, v123
	v_and_b32_e32 v123, 0xffff0000, v123
	v_lshlrev_b32_e32 v130, 16, v124
	v_and_b32_e32 v131, 0xffff0000, v124
	v_lshlrev_b32_e32 v124, 16, v125
	v_and_b32_e32 v125, 0xffff0000, v125
	v_pk_mul_f32 v[132:133], v[56:57], v[56:57]
	s_waitcnt lgkmcnt(3)
	v_pk_fma_f32 v[82:83], v[86:87], v[82:83], v[84:85]
	s_waitcnt lgkmcnt(2)
	v_pk_fma_f32 v[96:97], v[90:91], v[96:97], v[88:89]
	s_waitcnt lgkmcnt(1)
	v_pk_fma_f32 v[112:113], v[94:95], v[112:113], v[92:93]
	s_waitcnt lgkmcnt(0)
	v_pk_fma_f32 v[126:127], v[108:109], v[126:127], v[106:107]
	v_pk_fma_f32 v[84:85], v[86:87], v[128:129], v[84:85]
	v_pk_fma_f32 v[86:87], v[90:91], v[122:123], v[88:89]
	v_pk_fma_f32 v[88:89], v[94:95], v[130:131], v[92:93]
	v_pk_fma_f32 v[90:91], v[108:109], v[124:125], v[106:107]
	v_pk_fma_f32 v[82:83], v[208:209], v[82:83], v[206:207] op_sel_hi:[0,1,0]
	v_pk_fma_f32 v[92:93], v[208:209], v[96:97], v[206:207] op_sel_hi:[0,1,0]
	v_pk_fma_f32 v[94:95], v[208:209], v[112:113], v[206:207] op_sel_hi:[0,1,0]
	v_pk_fma_f32 v[96:97], v[208:209], v[126:127], v[206:207] op_sel_hi:[0,1,0]
	v_pk_fma_f32 v[84:85], v[202:203], v[84:85], v[204:205] op_sel_hi:[0,1,0]
	v_pk_fma_f32 v[106:107], v[202:203], v[86:87], v[204:205] op_sel_hi:[0,1,0]
	v_pk_fma_f32 v[108:109], v[202:203], v[88:89], v[204:205] op_sel_hi:[0,1,0]
	v_pk_fma_f32 v[90:91], v[202:203], v[90:91], v[204:205] op_sel_hi:[0,1,0]
	v_cvt_pk_bf16_f32 v86, v82, v83
	v_cvt_pk_bf16_f32 v87, v92, v93
	v_cvt_pk_bf16_f32 v88, v94, v95
	v_cvt_pk_bf16_f32 v89, v96, v97
	v_cvt_pk_bf16_f32 v82, v84, v85
	v_cvt_pk_bf16_f32 v83, v106, v107
	v_cvt_pk_bf16_f32 v84, v108, v109
	v_cvt_pk_bf16_f32 v85, v90, v91
	ds_read_b128 v[90:93], v110
	ds_read_b128 v[94:97], v110 offset:16
	ds_read_b128 v[106:109], v110 offset:32
	s_nop 0
	ds_read_b128 v[110:113], v110 offset:48
	v_lshlrev_b32_e32 v122, 16, v118
	v_and_b32_e32 v123, 0xffff0000, v118
	v_lshlrev_b32_e32 v118, 16, v119
	v_and_b32_e32 v119, 0xffff0000, v119
	v_lshlrev_b32_e32 v124, 16, v120
	v_and_b32_e32 v125, 0xffff0000, v120
	v_lshlrev_b32_e32 v120, 16, v121
	v_and_b32_e32 v121, 0xffff0000, v121
	v_lshlrev_b32_e32 v126, 16, v114
	v_and_b32_e32 v127, 0xffff0000, v114
	v_lshlrev_b32_e32 v114, 16, v115
	v_and_b32_e32 v115, 0xffff0000, v115
	v_lshlrev_b32_e32 v128, 16, v116
	v_and_b32_e32 v129, 0xffff0000, v116
	v_lshlrev_b32_e32 v116, 16, v117
	v_and_b32_e32 v117, 0xffff0000, v117
	v_pk_mul_f32 v[130:131], v[64:65], s[20:21] op_sel_hi:[1,0]
	v_pk_fma_f32 v[132:133], v[132:133], s[16:17], v[196:197] op_sel_hi:[1,0,0] neg_lo:[1,0,0] neg_hi:[1,0,0]
	v_pk_mul_f32 v[64:65], v[60:61], v[64:65]
	v_pk_mul_f32 v[56:57], v[56:57], v[132:133]
	s_waitcnt lgkmcnt(3)
; #define GAS __attribute__((address_space(1)))
; __device__ __forceinline__ float fexp2(float x) { return __builtin_amdgcn_exp2f(x); }
;     __device__ __forceinline__ void operator()(const af4 (&acc)[2][2][4][2], const pg8::Unit& u, int wr_, int wc_, int fr_, int fq_) const {
;     ...
;                 for (int n = 0; n < 2; ++n) {
;                     float vf[8];
;                     unpack8(raw[n][ks], vf);
; #pragma unroll
;                     for (int q = 0; q < 4; ++q) { f32x2 t = {vf[2 * q], vf[2 * q + 1]}; t = t * (f32x2){st[q].z, st[q].w} + (f32x2){st[q].x, st[q].y}; t = t * lg[n] + lb[n]; vf[2 * q] = t.x; vf[2 * q + 1] = t.y; }
;                     av[n][ks] = __builtin_bit_cast(bf16x8, pack8(vf));
;                 }
;             }
; #pragma unroll
;             for (int m = 0; m < 4; ++m) {
;                 if (ai == 0 && m == 0) load_raw(1);
;                 const int it = wr * 64 + m * 16 + fr;
;                 bf16x8 wf[4];
; #pragma unroll
;                 for (int ks = 0; ks < 4; ++ks) wf[ks] = *(const GAS bf16x8*)(wsg + (size_t)it * 128 + 32 * ks + 8 * fq);
;                 const float bsi = bs[grp * 128 + it];
;                 af4 vm[2] = {(af4){bsi, bsi, bsi, bsi}, (af4){bsi, bsi, bsi, bsi}};
; #pragma unroll
;                 for (int ks = 0; ks < 4; ++ks) {
; #pragma unroll
;                     for (int n = 0; n < 2; ++n) vm[n] = __builtin_amdgcn_mfma_f32_16x16x32_bf16(av[n][ks], wf[ks], vm[n], 0, 0, 0);
;                 }
;                 float o[8];
; #pragma unroll
;                 for (int n = 0; n < 2; ++n)
; #pragma unroll
;                     for (int e = 0; e < 4; e += 2) {
;                         const f32x2 uu = {acc[ai][0][m][n][e], acc[ai][0][m][n][e + 1]}, gg = {acc[ai][1][m][n][e], acc[ai][1][m][n][e + 1]}, vv = {vm[n][e], vm[n][e + 1]};
;                         const f32x2 ar = uu * (uu * uu * (-2.302208198f * 0.044715f) + (-2.302208198f));
;                         const f32x2 gs = gg * (-1.4426950408889634f);
;                         const f32x2 ea = {fexp2(ar.x), fexp2(ar.y)}, eb = {fexp2(gs.x), fexp2(gs.y)};
;                         const f32x2 q = eb + 1.0f, den = ea * q + q;
;                         const f32x2 r = {frcp(den.x), frcp(den.y)};
;                         const f32x2 w = (uu * gg) * vv * r;
;                         o[4 * n + e] = w.x; o[4 * n + e + 1] = w.y; }
	v_pk_fma_f32 v[122:123], v[92:93], v[122:123], v[90:91]
	s_waitcnt lgkmcnt(2)
	v_pk_fma_f32 v[118:119], v[96:97], v[118:119], v[94:95]
	s_waitcnt lgkmcnt(1)
	v_pk_fma_f32 v[124:125], v[108:109], v[124:125], v[106:107]
	s_waitcnt lgkmcnt(0)
	v_pk_fma_f32 v[120:121], v[112:113], v[120:121], v[110:111]
	v_pk_fma_f32 v[90:91], v[92:93], v[126:127], v[90:91]
	v_pk_fma_f32 v[92:93], v[96:97], v[114:115], v[94:95]
	v_pk_fma_f32 v[94:95], v[108:109], v[128:129], v[106:107]
	v_pk_fma_f32 v[96:97], v[112:113], v[116:117], v[110:111]
	v_pk_fma_f32 v[106:107], v[208:209], v[122:123], v[206:207] op_sel_hi:[0,1,0]
	v_pk_fma_f32 v[108:109], v[208:209], v[118:119], v[206:207] op_sel_hi:[0,1,0]
	v_pk_fma_f32 v[110:111], v[208:209], v[124:125], v[206:207] op_sel_hi:[0,1,0]
	v_pk_fma_f32 v[112:113], v[208:209], v[120:121], v[206:207] op_sel_hi:[0,1,0]
	v_pk_fma_f32 v[114:115], v[202:203], v[90:91], v[204:205] op_sel_hi:[0,1,0]
	v_pk_fma_f32 v[116:117], v[202:203], v[92:93], v[204:205] op_sel_hi:[0,1,0]
	v_pk_fma_f32 v[118:119], v[202:203], v[94:95], v[204:205] op_sel_hi:[0,1,0]
	v_pk_fma_f32 v[120:121], v[202:203], v[96:97], v[204:205] op_sel_hi:[0,1,0]
	v_cvt_pk_bf16_f32 v90, v106, v107
	v_cvt_pk_bf16_f32 v91, v108, v109
	v_cvt_pk_bf16_f32 v92, v110, v111
	v_cvt_pk_bf16_f32 v93, v112, v113
	v_cvt_pk_bf16_f32 v94, v114, v115
	v_cvt_pk_bf16_f32 v95, v116, v117
	v_cvt_pk_bf16_f32 v96, v118, v119
	v_cvt_pk_bf16_f32 v97, v120, v121
	s_waitcnt vmcnt(0)
	v_mov_b32_e32 v106, v250
	v_mov_b64_e32 v[110:111], v[234:235]
	v_mov_b64_e32 v[112:113], v[236:237]
	v_mov_b64_e32 v[114:115], v[238:239]
	v_mov_b64_e32 v[116:117], v[240:241]
	v_mov_b64_e32 v[118:119], v[242:243]
	v_mov_b64_e32 v[120:121], v[244:245]
	v_mov_b64_e32 v[122:123], v[246:247]
	v_mov_b64_e32 v[124:125], v[248:249]
	v_pk_mul_f32 v[108:109], v[60:61], v[60:61]
	v_pk_mul_f32 v[126:127], v[58:59], v[58:59]
	v_pk_mul_f32 v[128:129], v[62:63], s[20:21] op_sel_hi:[1,0]
	v_pk_fma_f32 v[52:53], v[126:127], s[16:17], v[196:197] op_sel_hi:[1,0,0] neg_lo:[1,0,0] neg_hi:[1,0,0]
	v_pk_fma_f32 v[108:109], v[108:109], s[16:17], v[196:197] op_sel_hi:[1,0,0] neg_lo:[1,0,0] neg_hi:[1,0,0]
	v_exp_f32_e32 v126, v128
	v_exp_f32_e32 v127, v129
	v_exp_f32_e32 v128, v130
	v_exp_f32_e32 v129, v131
	v_pk_fma_f32 v[130:131], v[134:135], s[16:17], v[196:197] op_sel_hi:[1,0,0] neg_lo:[1,0,0] neg_hi:[1,0,0]
	v_exp_f32_e32 v134, v136
	v_exp_f32_e32 v135, v137
	v_exp_f32_e32 v136, v50
	v_exp_f32_e32 v137, v51
	v_pk_mul_f32 v[50:51], v[58:59], v[52:53]
	v_pk_mul_f32 v[52:53], v[60:61], v[108:109]
	v_pk_mul_f32 v[62:63], v[58:59], v[62:63]
	v_pk_mul_f32 v[54:55], v[54:55], v[130:131]
	v_exp_f32_e32 v58, v50
	v_exp_f32_e32 v59, v51
	v_exp_f32_e32 v60, v52
	v_exp_f32_e32 v61, v53
	v_exp_f32_e32 v130, v54
	v_exp_f32_e32 v131, v55
	v_exp_f32_e32 v132, v56
	v_exp_f32_e32 v133, v57
	v_pk_add_f32 v[126:127], v[126:127], 1.0 op_sel_hi:[1,0]
	v_pk_add_f32 v[128:129], v[128:129], 1.0 op_sel_hi:[1,0]
	v_pk_add_f32 v[134:135], v[134:135], 1.0 op_sel_hi:[1,0]
	v_pk_add_f32 v[136:137], v[136:137], 1.0 op_sel_hi:[1,0]
	v_pk_fma_f32 v[58:59], v[58:59], v[126:127], v[126:127]
	v_pk_fma_f32 v[60:61], v[60:61], v[128:129], v[128:129]
	v_rcp_f32_e32 v58, v58
	v_rcp_f32_e32 v59, v59
	v_rcp_f32_e32 v60, v60
	v_rcp_f32_e32 v61, v61
	s_waitcnt vmcnt(4)
	v_mov_b32_e32 v107, v106
	v_mov_b32_e32 v108, v106
	v_mov_b32_e32 v109, v106
	s_waitcnt vmcnt(3)
	s_nop 0
	v_mfma_f32_16x16x32_bf16 v[50:53], v[70:73], v[110:113], v[106:109]
	v_mfma_f32_16x16x32_bf16 v[54:57], v[66:69], v[110:113], v[106:109]
	v_mad_i64_i32 v[110:111], s[26:27], v99, s61, v[198:199]
	v_lshl_add_u64 v[110:111], v[110:111], 0, s[40:41]
	s_waitcnt vmcnt(2)
	v_mfma_f32_16x16x32_bf16 v[50:53], v[78:81], v[114:117], v[50:53]
	v_fma_f32 v106, v130, v134, v134
	v_fma_f32 v107, v131, v135, v135
	v_pk_fma_f32 v[108:109], v[132:133], v[136:137], v[136:137]
	v_rcp_f32_e32 v106, v106
	v_mfma_f32_16x16x32_bf16 v[54:57], v[74:77], v[114:117], v[54:57]
	v_rcp_f32_e32 v107, v107
	v_rcp_f32_e32 v108, v108
	v_rcp_f32_e32 v109, v109
	s_waitcnt vmcnt(1)
	v_mfma_f32_16x16x32_bf16 v[50:53], v[86:89], v[118:121], v[50:53]
	v_lshl_add_u64 v[110:111], v[110:111], 0, s[6:7]
	v_lshl_add_u64 v[110:111], v[110:111], 0, v[186:187]
	v_pk_mul_f32 v[112:113], v[46:47], s[20:21] op_sel_hi:[1,0]
	v_mfma_f32_16x16x32_bf16 v[54:57], v[82:85], v[118:121], v[54:57]
	v_mul_f32_e64 v114, v48, s20
	v_mul_f32_e64 v115, v49, s20
	v_pk_mul_f32 v[116:117], v[40:41], v[40:41]
	v_pk_mul_f32 v[118:119], v[38:39], v[38:39]
	s_waitcnt vmcnt(0)
; #define GAS __attribute__((address_space(1)))
; __device__ __forceinline__ v4u pack8(const float (&f)[8]) { v4u w; w.x = pk2(f[0], f[1]); w.y = pk2(f[2], f[3]); w.z = pk2(f[4], f[5]); w.w = pk2(f[6], f[7]); return w; }
; __device__ __forceinline__ float fexp2(float x) { return __builtin_amdgcn_exp2f(x); }
; __device__ __forceinline__ float frcp(float x) { return __builtin_amdgcn_rcpf(x); }
;     __device__ __forceinline__ void operator()(const af4 (&acc)[2][2][4][2], const pg8::Unit& u, int wr_, int wc_, int fr_, int fq_) const {
;     ...
;             for (int m = 0; m < 4; ++m) {
;                 if (ai == 0 && m == 0) load_raw(1);
;                 const int it = wr * 64 + m * 16 + fr;
;                 bf16x8 wf[4];
; #pragma unroll
;                 for (int ks = 0; ks < 4; ++ks) wf[ks] = *(const GAS bf16x8*)(wsg + (size_t)it * 128 + 32 * ks + 8 * fq);
;                 const float bsi = bs[grp * 128 + it];
;                 af4 vm[2] = {(af4){bsi, bsi, bsi, bsi}, (af4){bsi, bsi, bsi, bsi}};
; #pragma unroll
;                 for (int ks = 0; ks < 4; ++ks) {
; #pragma unroll
;                     for (int n = 0; n < 2; ++n) vm[n] = __builtin_amdgcn_mfma_f32_16x16x32_bf16(av[n][ks], wf[ks], vm[n], 0, 0, 0);
;                 }
;                 float o[8];
; #pragma unroll
;                 for (int n = 0; n < 2; ++n)
; #pragma unroll
;                     for (int e = 0; e < 4; e += 2) {
;                         const f32x2 uu = {acc[ai][0][m][n][e], acc[ai][0][m][n][e + 1]}, gg = {acc[ai][1][m][n][e], acc[ai][1][m][n][e + 1]}, vv = {vm[n][e], vm[n][e + 1]};
;                         const f32x2 ar = uu * (uu * uu * (-2.302208198f * 0.044715f) + (-2.302208198f));
;                         const f32x2 gs = gg * (-1.4426950408889634f);
;                         const f32x2 ea = {fexp2(ar.x), fexp2(ar.y)}, eb = {fexp2(gs.x), fexp2(gs.y)};
;                         const f32x2 q = eb + 1.0f, den = ea * q + q;
;                         const f32x2 r = {frcp(den.x), frcp(den.y)};
;                         const f32x2 w = (uu * gg) * vv * r;
;                         o[4 * n + e] = w.x; o[4 * n + e + 1] = w.y; }
;                 *(GAS v4u*)(Y + (size_t)(tok0 + it) * CW + chbase + 32 * wc + 8 * fq) = pack8(o);
	v_mfma_f32_16x16x32_bf16 v[50:53], v[90:93], v[122:125], v[50:53]
	v_mul_f32_e64 v120, v34, s20
	v_mul_f32_e64 v121, v35, s20
	v_pk_fma_f32 v[116:117], v[116:117], s[16:17], v[196:197] op_sel_hi:[1,0,0] neg_lo:[1,0,0] neg_hi:[1,0,0]
	v_pk_mul_f32 v[46:47], v[42:43], v[46:47]
	v_mfma_f32_16x16x32_bf16 v[54:57], v[94:97], v[122:125], v[54:57]
	v_mul_f32_e64 v122, v38, v34
	v_mul_f32_e64 v123, v39, v35
	s_nop 0
	v_pk_mul_f32 v[50:51], v[62:63], v[50:51]
	v_pk_mul_f32 v[52:53], v[64:65], v[52:53]
	v_pk_mul_f32 v[50:51], v[58:59], v[50:51]
	v_pk_mul_f32 v[52:53], v[60:61], v[52:53]
	s_nop 0
	v_pk_mul_f32 v[54:55], v[138:139], v[54:55]
	v_pk_mul_f32 v[56:57], v[140:141], v[56:57]
	v_pk_mul_f32 v[54:55], v[106:107], v[54:55]
	v_pk_mul_f32 v[56:57], v[108:109], v[56:57]
	v_cvt_pk_bf16_f32 v50, v50, v51
	v_cvt_pk_bf16_f32 v51, v52, v53
	v_cvt_pk_bf16_f32 v52, v54, v55
	v_pk_mul_f32 v[34:35], v[36:37], s[20:21] op_sel_hi:[1,0]
	v_cvt_pk_bf16_f32 v53, v56, v57
	global_store_dwordx4 v[110:111], v[50:53], off
	s_nop 0
	s_nop 0
	ds_read_b128 v[54:57], v189 offset:0
	ds_read_b128 v[58:61], v189 offset:1024
	ds_read_b128 v[62:65], v189 offset:2048
	ds_read_b128 v[106:109], v189 offset:3072
	v_pk_mul_f32 v[52:53], v[44:45], v[44:45]
	v_pk_mul_f32 v[110:111], v[42:43], v[42:43]
	v_pk_mul_f32 v[124:125], v[40:41], v[36:37]
	v_pk_fma_f32 v[36:37], v[110:111], s[16:17], v[196:197] op_sel_hi:[1,0,0] neg_lo:[1,0,0] neg_hi:[1,0,0]
	v_pk_fma_f32 v[52:53], v[52:53], s[16:17], v[196:197] op_sel_hi:[1,0,0] neg_lo:[1,0,0] neg_hi:[1,0,0]
	v_exp_f32_e32 v110, v112
	v_exp_f32_e32 v111, v113
	v_exp_f32_e32 v112, v114
	v_exp_f32_e32 v113, v115
	v_pk_fma_f32 v[114:115], v[118:119], s[16:17], v[196:197] op_sel_hi:[1,0,0] neg_lo:[1,0,0] neg_hi:[1,0,0]
	v_exp_f32_e32 v118, v120
	v_exp_f32_e32 v119, v121
	v_exp_f32_e32 v120, v34
	v_exp_f32_e32 v121, v35
	v_pk_mul_f32 v[34:35], v[42:43], v[36:37]
	v_pk_mul_f32 v[36:37], v[44:45], v[52:53]
	v_pk_mul_f32 v[48:49], v[44:45], v[48:49]
	v_pk_mul_f32 v[38:39], v[38:39], v[114:115]
	v_pk_mul_f32 v[40:41], v[40:41], v[116:117]
	v_exp_f32_e32 v42, v34
	v_exp_f32_e32 v43, v35
	v_exp_f32_e32 v44, v36
	v_exp_f32_e32 v45, v37
	v_exp_f32_e32 v114, v38
	v_exp_f32_e32 v115, v39
	v_exp_f32_e32 v116, v40
	v_exp_f32_e32 v117, v41
	v_pk_add_f32 v[110:111], v[110:111], 1.0 op_sel_hi:[1,0]
	v_pk_add_f32 v[112:113], v[112:113], 1.0 op_sel_hi:[1,0]
	v_pk_add_f32 v[118:119], v[118:119], 1.0 op_sel_hi:[1,0]
	v_pk_add_f32 v[120:121], v[120:121], 1.0 op_sel_hi:[1,0]
	v_pk_fma_f32 v[42:43], v[42:43], v[110:111], v[110:111]
	v_pk_fma_f32 v[44:45], v[44:45], v[112:113], v[112:113]
	v_rcp_f32_e32 v42, v42
	v_rcp_f32_e32 v43, v43
	v_rcp_f32_e32 v44, v44
	v_rcp_f32_e32 v45, v45
	v_mov_b32_e32 v50, v179
	v_mov_b32_e32 v51, v50
	v_mov_b32_e32 v52, v50
	v_mov_b32_e32 v53, v50
	s_waitcnt lgkmcnt(3)
	s_nop 0
	v_mfma_f32_16x16x32_bf16 v[34:37], v[70:73], v[54:57], v[50:53]
	v_mfma_f32_16x16x32_bf16 v[38:41], v[66:69], v[54:57], v[50:53]
	v_add_u32_e32 v54, s23, v212
	v_mad_i64_i32 v[54:55], s[26:27], v54, s61, v[198:199]
	s_waitcnt lgkmcnt(2)
	v_mfma_f32_16x16x32_bf16 v[34:37], v[78:81], v[58:61], v[34:37]
	v_fma_f32 v50, v114, v118, v118
	v_fma_f32 v51, v115, v119, v119
	v_pk_fma_f32 v[52:53], v[116:117], v[120:121], v[120:121]
	v_rcp_f32_e32 v50, v50
	v_mfma_f32_16x16x32_bf16 v[38:41], v[74:77], v[58:61], v[38:41]
	v_rcp_f32_e32 v51, v51
	v_rcp_f32_e32 v52, v52
	v_rcp_f32_e32 v53, v53
	s_waitcnt lgkmcnt(1)
	v_mfma_f32_16x16x32_bf16 v[34:37], v[86:89], v[62:65], v[34:37]
	v_lshl_add_u64 v[54:55], v[54:55], 0, s[40:41]
	v_lshl_add_u64 v[54:55], v[54:55], 0, s[6:7]
	v_lshl_add_u64 v[54:55], v[54:55], 0, v[186:187]
	v_mfma_f32_16x16x32_bf16 v[38:41], v[82:85], v[62:65], v[38:41]
	v_mul_f32_e64 v56, v30, s20
	v_mul_f32_e64 v57, v31, s20
	v_pk_mul_f32 v[58:59], v[32:33], s[20:21] op_sel_hi:[1,0]
	v_pk_mul_f32 v[60:61], v[24:25], v[24:25]
	s_waitcnt lgkmcnt(0)
	v_mfma_f32_16x16x32_bf16 v[34:37], v[90:93], v[106:109], v[34:37]
	v_mul_f32_e64 v62, v22, v22
	v_mul_f32_e64 v63, v23, v23
	v_pk_mul_f32 v[64:65], v[18:19], s[20:21] op_sel_hi:[1,0]
	v_pk_fma_f32 v[60:61], v[60:61], s[16:17], v[196:197] op_sel_hi:[1,0,0] neg_lo:[1,0,0] neg_hi:[1,0,0]
	v_mfma_f32_16x16x32_bf16 v[38:41], v[94:97], v[106:109], v[38:41]
	v_mul_f32_e64 v106, v24, v20
	v_mul_f32_e64 v107, v25, v21
	s_nop 0
	v_pk_mul_f32 v[34:35], v[46:47], v[34:35]
	v_pk_mul_f32 v[36:37], v[48:49], v[36:37]
	v_pk_mul_f32 v[34:35], v[42:43], v[34:35]
	v_pk_mul_f32 v[36:37], v[44:45], v[36:37]
	s_nop 0
	v_pk_mul_f32 v[38:39], v[122:123], v[38:39]
	v_pk_mul_f32 v[40:41], v[124:125], v[40:41]
	v_pk_mul_f32 v[38:39], v[50:51], v[38:39]
	v_pk_mul_f32 v[40:41], v[52:53], v[40:41]
	v_cvt_pk_bf16_f32 v34, v34, v35
	v_cvt_pk_bf16_f32 v35, v36, v37
	v_cvt_pk_bf16_f32 v36, v38, v39
	v_pk_mul_f32 v[30:31], v[26:27], v[30:31]
	v_cvt_pk_bf16_f32 v37, v40, v41
	global_store_dwordx4 v[54:55], v[34:37], off
	s_nop 0
	s_nop 0
	ds_read_b128 v[38:41], v189 offset:4096
	ds_read_b128 v[42:45], v189 offset:5120
	ds_read_b128 v[46:49], v189 offset:6144
	ds_read_b128 v[50:53], v189 offset:7168
	v_pk_mul_f32 v[36:37], v[28:29], v[28:29]
	v_pk_mul_f32 v[54:55], v[26:27], v[26:27]
	v_pk_mul_f32 v[102:103], v[22:23], v[18:19]
	v_pk_mul_f32 v[18:19], v[20:21], s[20:21] op_sel_hi:[1,0]
	v_pk_fma_f32 v[20:21], v[54:55], s[16:17], v[196:197] op_sel_hi:[1,0,0] neg_lo:[1,0,0] neg_hi:[1,0,0]
	v_pk_fma_f32 v[36:37], v[36:37], s[16:17], v[196:197] op_sel_hi:[1,0,0] neg_lo:[1,0,0] neg_hi:[1,0,0]
	v_exp_f32_e32 v54, v56
	v_exp_f32_e32 v55, v57
	v_exp_f32_e32 v56, v58
	v_exp_f32_e32 v57, v59
	v_pk_fma_f32 v[58:59], v[62:63], s[16:17], v[196:197] op_sel_hi:[1,0,0] neg_lo:[1,0,0] neg_hi:[1,0,0]
	v_exp_f32_e32 v62, v64
	v_exp_f32_e32 v63, v65
	v_exp_f32_e32 v64, v18
	v_exp_f32_e32 v65, v19
	v_pk_mul_f32 v[18:19], v[26:27], v[20:21]
	v_pk_mul_f32 v[20:21], v[28:29], v[36:37]
	v_pk_mul_f32 v[32:33], v[28:29], v[32:33]
	v_pk_mul_f32 v[22:23], v[22:23], v[58:59]
	v_pk_mul_f32 v[24:25], v[24:25], v[60:61]
	v_exp_f32_e32 v26, v18
	v_exp_f32_e32 v27, v19
	v_exp_f32_e32 v28, v20
	v_exp_f32_e32 v29, v21
	v_exp_f32_e32 v58, v22
	v_exp_f32_e32 v59, v23
	v_exp_f32_e32 v60, v24
	v_exp_f32_e32 v61, v25
	v_pk_add_f32 v[54:55], v[54:55], 1.0 op_sel_hi:[1,0]
	v_pk_add_f32 v[56:57], v[56:57], 1.0 op_sel_hi:[1,0]
	v_pk_add_f32 v[62:63], v[62:63], 1.0 op_sel_hi:[1,0]
	v_pk_add_f32 v[64:65], v[64:65], 1.0 op_sel_hi:[1,0]
	v_pk_fma_f32 v[26:27], v[26:27], v[54:55], v[54:55]
	v_pk_fma_f32 v[28:29], v[28:29], v[56:57], v[56:57]
	v_rcp_f32_e32 v26, v26
	v_rcp_f32_e32 v27, v27
	v_rcp_f32_e32 v28, v28
	v_rcp_f32_e32 v29, v29
	v_mov_b32_e32 v34, v181
	v_mov_b32_e32 v35, v34
	v_mov_b32_e32 v36, v34
	v_mov_b32_e32 v37, v34
	s_waitcnt lgkmcnt(3)
; template <class Epi, class Sched, bool ALIGN_EPI = false, bool SP2 = false>
; __device__ __forceinline__ void gemm_phase(PG8_LAS unsigned char* lds, const Gemm g, const Sched& S, const Epi& E) {
;     ...
;         if constexpr (ALIGN_EPI) { if (wr == 0) PG8_BAR; }
;         E(acc, cur, wr, wc, fr, fq);
;         if (!has_next) break;
; #pragma unroll
;         for (int a = 0; a < 2; ++a)
; #pragma unroll
;             for (int b = 0; b < 2; ++b)
; #pragma unroll
;                 for (int m = 0; m < 4; ++m)
; #pragma unroll
;     __device__ __forceinline__ void operator()(const af4 (&acc)[2][2][4][2], const pg8::Unit& u, int wr_, int wc_, int fr_, int fq_) const {
;     ...
;             for (int m = 0; m < 4; ++m) {
;                 if (ai == 0 && m == 0) load_raw(1);
;                 const int it = wr * 64 + m * 16 + fr;
;                 bf16x8 wf[4];
; #pragma unroll
;                 for (int ks = 0; ks < 4; ++ks) wf[ks] = *(const GAS bf16x8*)(wsg + (size_t)it * 128 + 32 * ks + 8 * fq);
;                 const float bsi = bs[grp * 128 + it];
;                 af4 vm[2] = {(af4){bsi, bsi, bsi, bsi}, (af4){bsi, bsi, bsi, bsi}};
; #pragma unroll
;                 for (int ks = 0; ks < 4; ++ks) {
; #pragma unroll
;                     for (int n = 0; n < 2; ++n) vm[n] = __builtin_amdgcn_mfma_f32_16x16x32_bf16(av[n][ks], wf[ks], vm[n], 0, 0, 0);
;                 }
;                 float o[8];
; #pragma unroll
;                 for (int n = 0; n < 2; ++n)
; #pragma unroll
;                     for (int e = 0; e < 4; e += 2) {
;                         const f32x2 uu = {acc[ai][0][m][n][e], acc[ai][0][m][n][e + 1]}, gg = {acc[ai][1][m][n][e], acc[ai][1][m][n][e + 1]}, vv = {vm[n][e], vm[n][e + 1]};
;                         const f32x2 ar = uu * (uu * uu * (-2.302208198f * 0.044715f) + (-2.302208198f));
;                         const f32x2 gs = gg * (-1.4426950408889634f);
;                         const f32x2 ea = {fexp2(ar.x), fexp2(ar.y)}, eb = {fexp2(gs.x), fexp2(gs.y)};
;                         const f32x2 q = eb + 1.0f, den = ea * q + q;
;                         const f32x2 r = {frcp(den.x), frcp(den.y)};
;                         const f32x2 w = (uu * gg) * vv * r;
;                         o[4 * n + e] = w.x; o[4 * n + e + 1] = w.y; }
;                 *(GAS v4u*)(Y + (size_t)(tok0 + it) * CW + chbase + 32 * wc + 8 * fq) = pack8(o);
;             }
	s_nop 0
	v_mfma_f32_16x16x32_bf16 v[18:21], v[70:73], v[38:41], v[34:37]
	v_mfma_f32_16x16x32_bf16 v[22:25], v[66:69], v[38:41], v[34:37]
	v_add_u32_e32 v38, s23, v98
	v_mad_i64_i32 v[38:39], s[26:27], v38, s61, v[198:199]
	s_waitcnt lgkmcnt(2)
	v_mfma_f32_16x16x32_bf16 v[18:21], v[78:81], v[42:45], v[18:21]
	v_fma_f32 v34, v58, v62, v62
	v_fma_f32 v35, v59, v63, v63
	v_pk_fma_f32 v[36:37], v[60:61], v[64:65], v[64:65]
	v_rcp_f32_e32 v34, v34
	v_mfma_f32_16x16x32_bf16 v[22:25], v[74:77], v[42:45], v[22:25]
	v_rcp_f32_e32 v35, v35
	v_rcp_f32_e32 v36, v36
	v_rcp_f32_e32 v37, v37
	s_waitcnt lgkmcnt(1)
	v_mfma_f32_16x16x32_bf16 v[18:21], v[86:89], v[46:49], v[18:21]
	v_lshl_add_u64 v[38:39], v[38:39], 0, s[40:41]
	v_lshl_add_u64 v[38:39], v[38:39], 0, s[6:7]
	v_lshl_add_u64 v[38:39], v[38:39], 0, v[186:187]
	v_mfma_f32_16x16x32_bf16 v[22:25], v[82:85], v[46:49], v[22:25]
	v_mul_f32_e64 v40, v14, s20
	v_mul_f32_e64 v41, v15, s20
	v_pk_mul_f32 v[42:43], v[16:17], s[20:21] op_sel_hi:[1,0]
	v_pk_mul_f32 v[44:45], v[8:9], v[8:9]
	s_waitcnt lgkmcnt(0)
	v_mfma_f32_16x16x32_bf16 v[18:21], v[90:93], v[50:53], v[18:21]
	v_mul_f32_e64 v46, v6, v6
	v_mul_f32_e64 v47, v7, v7
	v_pk_mul_f32 v[48:49], v[2:3], s[20:21] op_sel_hi:[1,0]
	v_pk_fma_f32 v[44:45], v[44:45], s[16:17], v[196:197] op_sel_hi:[1,0,0] neg_lo:[1,0,0] neg_hi:[1,0,0]
	v_mfma_f32_16x16x32_bf16 v[22:25], v[94:97], v[50:53], v[22:25]
	v_mul_f32_e64 v50, v6, v2
	v_mul_f32_e64 v51, v7, v3
	s_nop 0
	v_pk_mul_f32 v[18:19], v[30:31], v[18:19]
	v_pk_mul_f32 v[20:21], v[32:33], v[20:21]
	v_pk_mul_f32 v[18:19], v[26:27], v[18:19]
	v_pk_mul_f32 v[20:21], v[28:29], v[20:21]
	s_nop 0
	v_pk_mul_f32 v[22:23], v[102:103], v[22:23]
	v_pk_mul_f32 v[24:25], v[106:107], v[24:25]
	v_pk_mul_f32 v[22:23], v[34:35], v[22:23]
	v_pk_mul_f32 v[24:25], v[36:37], v[24:25]
	v_cvt_pk_bf16_f32 v18, v18, v19
	v_cvt_pk_bf16_f32 v19, v20, v21
	v_cvt_pk_bf16_f32 v20, v22, v23
	v_pk_mul_f32 v[2:3], v[4:5], s[20:21] op_sel_hi:[1,0]
	v_cvt_pk_bf16_f32 v21, v24, v25
	global_store_dwordx4 v[38:39], v[18:21], off
	s_nop 0
	s_nop 0
	ds_read_b128 v[22:25], v189 offset:8192
	ds_read_b128 v[26:29], v189 offset:9216
	ds_read_b128 v[30:33], v189 offset:10240
	ds_read_b128 v[34:37], v189 offset:11264
	v_pk_mul_f32 v[20:21], v[12:13], v[12:13]
	v_pk_mul_f32 v[38:39], v[10:11], v[10:11]
	v_pk_mul_f32 v[52:53], v[8:9], v[4:5]
	v_pk_fma_f32 v[4:5], v[38:39], s[16:17], v[196:197] op_sel_hi:[1,0,0] neg_lo:[1,0,0] neg_hi:[1,0,0]
	v_pk_fma_f32 v[20:21], v[20:21], s[16:17], v[196:197] op_sel_hi:[1,0,0] neg_lo:[1,0,0] neg_hi:[1,0,0]
	v_exp_f32_e32 v38, v40
	v_exp_f32_e32 v39, v41
	v_exp_f32_e32 v40, v42
	v_exp_f32_e32 v41, v43
	v_pk_fma_f32 v[42:43], v[46:47], s[16:17], v[196:197] op_sel_hi:[1,0,0] neg_lo:[1,0,0] neg_hi:[1,0,0]
	v_exp_f32_e32 v46, v48
	v_exp_f32_e32 v47, v49
	v_exp_f32_e32 v48, v2
	v_exp_f32_e32 v49, v3
	v_pk_mul_f32 v[2:3], v[10:11], v[4:5]
	v_pk_mul_f32 v[4:5], v[12:13], v[20:21]
	v_pk_mul_f32 v[14:15], v[10:11], v[14:15]
	v_pk_mul_f32 v[16:17], v[12:13], v[16:17]
	v_pk_mul_f32 v[6:7], v[6:7], v[42:43]
	v_pk_mul_f32 v[8:9], v[8:9], v[44:45]
	v_exp_f32_e32 v10, v2
	v_exp_f32_e32 v11, v3
	v_exp_f32_e32 v12, v4
	v_exp_f32_e32 v13, v5
	v_exp_f32_e32 v42, v6
	v_exp_f32_e32 v43, v7
	v_exp_f32_e32 v44, v8
	v_exp_f32_e32 v45, v9
	v_pk_add_f32 v[38:39], v[38:39], 1.0 op_sel_hi:[1,0]
	v_pk_add_f32 v[40:41], v[40:41], 1.0 op_sel_hi:[1,0]
	v_pk_add_f32 v[46:47], v[46:47], 1.0 op_sel_hi:[1,0]
	v_pk_add_f32 v[48:49], v[48:49], 1.0 op_sel_hi:[1,0]
	v_pk_fma_f32 v[10:11], v[10:11], v[38:39], v[38:39]
	v_pk_fma_f32 v[12:13], v[12:13], v[40:41], v[40:41]
	v_rcp_f32_e32 v10, v10
	v_rcp_f32_e32 v11, v11
	v_rcp_f32_e32 v12, v12
	v_rcp_f32_e32 v13, v13
	v_mov_b32_e32 v18, v183
	v_mov_b32_e32 v19, v18
	v_mov_b32_e32 v20, v18
	v_mov_b32_e32 v21, v18
	s_waitcnt lgkmcnt(3)
	s_nop 0
	v_mfma_f32_16x16x32_bf16 v[2:5], v[70:73], v[22:25], v[18:21]
	v_mfma_f32_16x16x32_bf16 v[6:9], v[66:69], v[22:25], v[18:21]
	v_add_u32_e32 v22, s23, v100
	v_mad_i64_i32 v[22:23], s[4:5], v22, s61, v[198:199]
	s_waitcnt lgkmcnt(2)
	v_mfma_f32_16x16x32_bf16 v[2:5], v[78:81], v[26:29], v[2:5]
	v_fma_f32 v18, v42, v46, v46
	v_fma_f32 v19, v43, v47, v47
	v_pk_fma_f32 v[20:21], v[44:45], v[48:49], v[48:49]
	v_rcp_f32_e32 v18, v18
	v_mfma_f32_16x16x32_bf16 v[6:9], v[74:77], v[26:29], v[6:9]
	v_rcp_f32_e32 v19, v19
	v_rcp_f32_e32 v20, v20
	v_rcp_f32_e32 v21, v21
	s_waitcnt lgkmcnt(1)
	v_mfma_f32_16x16x32_bf16 v[2:5], v[86:89], v[30:33], v[2:5]
	v_lshl_add_u64 v[22:23], v[22:23], 0, s[40:41]
	v_lshl_add_u64 v[22:23], v[22:23], 0, s[6:7]
	v_lshl_add_u64 v[22:23], v[22:23], 0, v[186:187]
	v_mfma_f32_16x16x32_bf16 v[6:9], v[82:85], v[30:33], v[6:9]
	s_mov_b64 s[4:5], -1
	s_waitcnt lgkmcnt(0)
	v_mfma_f32_16x16x32_bf16 v[2:5], v[90:93], v[34:37], v[2:5]
	v_mfma_f32_16x16x32_bf16 v[6:9], v[94:97], v[34:37], v[6:9]
	s_nop 6
	v_mul_f32_e64 v2, v14, v2
	v_mul_f32_e64 v3, v15, v3
	v_pk_mul_f32 v[4:5], v[16:17], v[4:5]
	v_pk_mul_f32 v[6:7], v[50:51], v[6:7]
	v_pk_mul_f32 v[8:9], v[52:53], v[8:9]
	v_pk_mul_f32 v[2:3], v[10:11], v[2:3]
	v_pk_mul_f32 v[4:5], v[12:13], v[4:5]
	v_pk_mul_f32 v[6:7], v[18:19], v[6:7]
	v_pk_mul_f32 v[8:9], v[20:21], v[8:9]
	v_cvt_pk_bf16_f32 v2, v2, v3
	v_cvt_pk_bf16_f32 v3, v4, v5
	v_cvt_pk_bf16_f32 v4, v6, v7
	s_nop 0
	v_cvt_pk_bf16_f32 v5, v8, v9
	global_store_dwordx4 v[22:23], v[2:5], off
	s_cbranch_vccnz .LBB0_1123
	s_andn2_b64 vcc, exec, s[10:11]
	s_cbranch_vccnz .LBB0_1122
	s_barrier
	s_branch .LBB0_1122
